# combine phase: slotmap word and router gate of the next row group prefetched one iteration ahead; loop top waits vmcnt(8) instead of draining stores
# baseline (speedup 1.0000x reference)
.LBB0_931:
	s_or_b64 exec, exec, s[4:5]
	v_and_b32_e32 v2, 63, v0
	s_cmpk_lt_i32 s54, 0x2200
	s_waitcnt lgkmcnt(0)
	s_barrier
	s_cbranch_scc0 .LBB0_942
	v_and_b32_e32 v1, 15, v2
	v_ashrrev_i32_e32 v165, 4, v2
	v_and_b32_e32 v164, -16, v2
	v_mov_b32_e32 v2, 0
	v_lshlrev_b32_e32 v6, 3, v1
	v_mov_b32_e32 v7, v2
	v_lshl_add_u64 v[168:169], s[68:69], 0, v[6:7]
	v_mbcnt_lo_u32_b32 v6, -1, 0
	v_mbcnt_hi_u32_b32 v6, -1, v6
	v_and_b32_e32 v184, 64, v6
	v_xor_b32_e32 v7, 1, v6
	v_add_u32_e32 v8, 64, v184
	v_cmp_lt_i32_e32 vcc, v7, v8
	v_readlane_b32 s4, v255, 8
	v_lshlrev_b32_e32 v3, 5, v1
	v_cndmask_b32_e32 v7, v6, v7, vcc
	v_lshlrev_b32_e32 v185, 2, v7
	v_xor_b32_e32 v7, 2, v6
	v_cmp_lt_i32_e32 vcc, v7, v8
	v_lshlrev_b32_e32 v4, 4, v1
	v_mov_b32_e32 v5, v2
	v_cndmask_b32_e32 v7, v6, v7, vcc
	v_lshlrev_b32_e32 v186, 2, v7
	v_xor_b32_e32 v7, 4, v6
	v_cmp_lt_i32_e32 vcc, v7, v8
	v_readlane_b32 s5, v255, 9
	v_add_u32_e32 v181, s3, v3
	v_cndmask_b32_e32 v7, v6, v7, vcc
	v_lshlrev_b32_e32 v187, 2, v7
	v_xor_b32_e32 v7, 8, v6
	v_cmp_lt_i32_e32 vcc, v7, v8
	v_lshl_add_u64 v[166:167], s[66:67], 0, v[4:5]
	v_add_u32_e32 v189, 0, v3
	v_cndmask_b32_e32 v6, v6, v7, vcc
	v_lshlrev_b32_e32 v188, 2, v6
	v_lshl_add_u64 v[170:171], s[4:5], 0, v[4:5]
	s_mov_b32 s3, 0xffff0000
	s_movk_i32 s6, 0x7fff
	v_mov_b32_e32 v190, 0x358637bd
	s_mov_b32 s7, 0xf800000
	v_mov_b32_e32 v191, 0x260
	s_mov_b32 s8, s54
	v_lshl_add_u32 v252, s8, 2, v165
	v_lshl_or_b32 v252, v252, 4, v1
	v_ashrrev_i32_e32 v253, 31, v252
	v_lshl_add_u64 v[252:253], v[252:253], 2, s[64:65]
	global_load_dword v250, v[252:253], off
	s_waitcnt vmcnt(0)
	v_max_i32_e32 v252, 0, v250
	v_min_u32_e32 v252, 0x10fff, v252
	v_mov_b32_e32 v253, 0
	v_lshl_add_u64 v[252:253], v[252:253], 2, s[62:63]
	global_load_dword v251, v[252:253], off
	s_waitcnt vmcnt(0)
	s_branch .LBB0_934
.LBB0_933:
	v_min_i32_e32 v3, 0x8000, v176
	v_and_b32_e32 v3, 0xfffff000, v3
	s_waitcnt vmcnt(5)
	v_lshlrev_b32_e32 v148, 16, v88
	v_and_b32_e32 v149, 0xffff0000, v88
	v_add_u32_e32 v88, v181, v3
	s_waitcnt vmcnt(1)
	v_lshlrev_b32_e32 v112, 16, v68
	v_lshlrev_b32_e32 v114, 16, v69
	v_lshlrev_b32_e32 v108, 16, v70
	v_lshlrev_b32_e32 v110, 16, v71
	v_and_b32_e32 v113, 0xffff0000, v68
	v_and_b32_e32 v115, 0xffff0000, v69
	v_and_b32_e32 v109, 0xffff0000, v70
	v_and_b32_e32 v111, 0xffff0000, v71
	ds_read_b128 v[68:71], v88
	v_lshlrev_b32_e32 v120, 16, v72
	v_lshlrev_b32_e32 v122, 16, v73
	v_lshlrev_b32_e32 v116, 16, v74
	v_lshlrev_b32_e32 v118, 16, v75
	v_and_b32_e32 v121, 0xffff0000, v72
	v_and_b32_e32 v123, 0xffff0000, v73
	v_and_b32_e32 v117, 0xffff0000, v74
	v_and_b32_e32 v119, 0xffff0000, v75
	ds_read_b128 v[72:75], v88 offset:16
	v_lshlrev_b32_e32 v132, 16, v96
	v_lshlrev_b32_e32 v134, 16, v97
	v_and_b32_e32 v133, 0xffff0000, v96
	v_and_b32_e32 v135, 0xffff0000, v97
	s_waitcnt vmcnt(0)
	v_max_i32_e32 v252, 0, v250
	v_min_u32_e32 v252, 0x10fff, v252
	v_mov_b32_e32 v253, 0
	v_lshl_add_u64 v[252:253], v[252:253], 2, s[62:63]
	global_load_dword v251, v[252:253], off
	v_lshlrev_b32_e32 v104, 16, v60
	v_lshlrev_b32_e32 v106, 16, v61
	v_lshlrev_b32_e32 v100, 16, v62
	v_lshlrev_b32_e32 v102, 16, v63
	v_and_b32_e32 v105, 0xffff0000, v60
	v_and_b32_e32 v107, 0xffff0000, v61
	v_and_b32_e32 v101, 0xffff0000, v62
	v_and_b32_e32 v103, 0xffff0000, v63
	s_waitcnt lgkmcnt(1)
	v_pk_fma_f32 v[60:61], v[86:87], v[70:71], v[134:135]
	v_pk_fma_f32 v[62:63], v[84:85], v[68:69], v[132:133]
	v_pk_mul_f32 v[68:69], v[60:61], v[60:61]
	v_pk_mul_f32 v[70:71], v[62:63], v[62:63]
	v_lshlrev_b32_e32 v136, 16, v98
	v_lshlrev_b32_e32 v138, 16, v99
	v_lshlrev_b32_e32 v128, 16, v76
	v_lshlrev_b32_e32 v130, 16, v77
	v_and_b32_e32 v137, 0xffff0000, v98
	v_and_b32_e32 v139, 0xffff0000, v99
	v_and_b32_e32 v129, 0xffff0000, v76
	v_and_b32_e32 v131, 0xffff0000, v77
	v_pk_mov_b32 v[76:77], v[70:71], v[68:69] op_sel:[1,0]
	v_mov_b32_e32 v71, v69
	v_pk_add_f32 v[76:77], v[76:77], v[70:71]
	s_waitcnt lgkmcnt(0)
	v_pk_fma_f32 v[66:67], v[66:67], v[74:75], v[138:139]
	v_pk_fma_f32 v[64:65], v[64:65], v[72:73], v[136:137]
	ds_read_b128 v[68:71], v88 offset:512
	ds_read_b128 v[72:75], v88 offset:528
	v_lshlrev_b32_e32 v144, 16, v94
	v_lshlrev_b32_e32 v156, 16, v80
	v_lshlrev_b32_e32 v158, 16, v81
	v_lshlrev_b32_e32 v124, 16, v78
	v_lshlrev_b32_e32 v126, 16, v79
	v_and_b32_e32 v145, 0xffff0000, v94
	v_and_b32_e32 v157, 0xffff0000, v80
	v_and_b32_e32 v159, 0xffff0000, v81
	v_and_b32_e32 v125, 0xffff0000, v78
	v_and_b32_e32 v127, 0xffff0000, v79
	v_pk_mul_f32 v[78:79], v[66:67], v[66:67]
	v_pk_mul_f32 v[80:81], v[64:65], v[64:65]
	v_lshlrev_b32_e32 v140, 16, v92
	v_lshlrev_b32_e32 v142, 16, v93
	v_lshlrev_b32_e32 v160, 16, v82
	v_lshlrev_b32_e32 v162, 16, v83
	v_and_b32_e32 v141, 0xffff0000, v92
	v_and_b32_e32 v143, 0xffff0000, v93
	v_and_b32_e32 v161, 0xffff0000, v82
	v_and_b32_e32 v163, 0xffff0000, v83
	v_pk_mov_b32 v[82:83], v[80:81], v[78:79] op_sel:[1,0]
	v_mov_b32_e32 v81, v79
	s_waitcnt lgkmcnt(0)
	v_pk_fma_f32 v[52:53], v[52:53], v[72:73], v[144:145]
	v_pk_add_f32 v[78:79], v[82:83], v[80:81]
	v_pk_fma_f32 v[58:59], v[58:59], v[70:71], v[142:143]
	v_pk_fma_f32 v[56:57], v[56:57], v[68:69], v[140:141]
	v_mul_f32_e32 v70, v52, v52
	v_pk_add_f32 v[68:69], v[76:77], v[76:77] op_sel:[0,1] op_sel_hi:[1,0]
	v_mul_f32_e32 v72, v53, v53
	v_mov_b32_e32 v69, v70
	v_pk_add_f32 v[70:71], v[78:79], v[78:79] op_sel:[0,1] op_sel_hi:[1,0]
	v_lshlrev_b32_e32 v146, 16, v95
	v_mov_b32_e32 v71, v72
	v_and_b32_e32 v147, 0xffff0000, v95
	v_pk_add_f32 v[72:73], v[68:69], v[70:71]
	v_mul_f32_e32 v68, v57, v57
	v_pk_fma_f32 v[54:55], v[54:55], v[74:75], v[146:147]
	v_pk_fma_f32 v[74:75], v[56:57], v[56:57], v[68:69] op_sel_hi:[1,1,0]
	v_mul_f32_e32 v68, v59, v59
	v_pk_fma_f32 v[76:77], v[58:59], v[58:59], v[68:69] op_sel_hi:[1,1,0]
	ds_read_b128 v[68:71], v88 offset:1024
	v_mul_f32_e32 v80, v54, v54
	v_mul_f32_e32 v81, v55, v55
	v_mov_b32_e32 v75, v80
	v_mov_b32_e32 v77, v81
	v_lshlrev_b32_e32 v150, 16, v89
	v_and_b32_e32 v151, 0xffff0000, v89
	v_pk_add_f32 v[74:75], v[74:75], v[76:77]
	v_lshlrev_b32_e32 v152, 16, v90
	v_pk_add_f32 v[76:77], v[72:73], v[74:75]
	ds_read_b128 v[72:75], v88 offset:1040
	s_waitcnt lgkmcnt(1)
	v_pk_fma_f32 v[50:51], v[50:51], v[70:71], v[150:151]
	v_pk_fma_f32 v[48:49], v[48:49], v[68:69], v[148:149]
	v_pk_mul_f32 v[68:69], v[50:51], v[50:51]
	v_pk_mul_f32 v[78:79], v[48:49], v[48:49]
	v_lshlrev_b32_e32 v154, 16, v91
	v_pk_mov_b32 v[80:81], v[78:79], v[68:69] op_sel:[1,0]
	v_mov_b32_e32 v79, v69
	ds_read_b128 v[68:71], v88 offset:1536
	v_and_b32_e32 v153, 0xffff0000, v90
	v_and_b32_e32 v155, 0xffff0000, v91
	s_waitcnt lgkmcnt(1)
	v_pk_fma_f32 v[46:47], v[46:47], v[74:75], v[154:155]
	v_pk_fma_f32 v[44:45], v[44:45], v[72:73], v[152:153]
	ds_read_b128 v[72:75], v88 offset:1552
	s_waitcnt lgkmcnt(1)
	v_pk_fma_f32 v[40:41], v[40:41], v[68:69], v[156:157]
	v_pk_add_f32 v[78:79], v[80:81], v[78:79]
	v_pk_fma_f32 v[42:43], v[42:43], v[70:71], v[158:159]
	v_mul_f32_e32 v70, v40, v40
	v_pk_add_f32 v[68:69], v[76:77], v[76:77] op_sel:[0,1] op_sel_hi:[1,0]
	v_mul_f32_e32 v80, v41, v41
	v_mov_b32_e32 v69, v70
	v_pk_add_f32 v[70:71], v[78:79], v[78:79] op_sel:[0,1] op_sel_hi:[1,0]
	v_mul_f32_e32 v76, v47, v47
	v_mov_b32_e32 v71, v80
	v_pk_add_f32 v[68:69], v[68:69], v[70:71]
	v_mul_f32_e32 v70, v45, v45
	v_mul_f32_e32 v81, v42, v42
	v_mul_f32_e32 v82, v43, v43
	v_pk_fma_f32 v[70:71], v[44:45], v[44:45], v[70:71] op_sel_hi:[1,1,0]
	v_pk_fma_f32 v[76:77], v[46:47], v[46:47], v[76:77] op_sel_hi:[1,1,0]
	v_mov_b32_e32 v71, v81
	v_mov_b32_e32 v77, v82
	v_pk_add_f32 v[70:71], v[70:71], v[76:77]
	s_waitcnt lgkmcnt(0)
	v_pk_fma_f32 v[38:39], v[38:39], v[74:75], v[162:163]
	v_pk_add_f32 v[76:77], v[68:69], v[70:71]
	v_pk_fma_f32 v[36:37], v[36:37], v[72:73], v[160:161]
	ds_read_b128 v[68:71], v88 offset:2048
	ds_read_b128 v[72:75], v88 offset:2064
	v_pk_mul_f32 v[78:79], v[38:39], v[38:39]
	v_pk_mul_f32 v[80:81], v[36:37], v[36:37]
	v_add_u32_e32 v3, v189, v3
	v_pk_mov_b32 v[82:83], v[80:81], v[78:79] op_sel:[1,0]
	v_mov_b32_e32 v81, v79
	s_waitcnt lgkmcnt(0)
	v_pk_fma_f32 v[28:29], v[28:29], v[72:73], v[124:125]
	v_pk_add_f32 v[78:79], v[82:83], v[80:81]
	v_pk_fma_f32 v[34:35], v[34:35], v[70:71], v[130:131]
	v_pk_fma_f32 v[32:33], v[32:33], v[68:69], v[128:129]
	v_mul_f32_e32 v70, v28, v28
	v_pk_add_f32 v[68:69], v[76:77], v[76:77] op_sel:[0,1] op_sel_hi:[1,0]
	v_mul_f32_e32 v72, v29, v29
	v_mov_b32_e32 v69, v70
	v_pk_add_f32 v[70:71], v[78:79], v[78:79] op_sel:[0,1] op_sel_hi:[1,0]
	v_pk_fma_f32 v[30:31], v[30:31], v[74:75], v[126:127]
	v_mov_b32_e32 v71, v72
	v_pk_add_f32 v[72:73], v[68:69], v[70:71]
	v_mul_f32_e32 v68, v33, v33
	v_pk_fma_f32 v[74:75], v[32:33], v[32:33], v[68:69] op_sel_hi:[1,1,0]
	v_mul_f32_e32 v68, v35, v35
	v_pk_fma_f32 v[76:77], v[34:35], v[34:35], v[68:69] op_sel_hi:[1,1,0]
	ds_read_b128 v[68:71], v88 offset:2560
	v_mul_f32_e32 v80, v30, v30
	v_mul_f32_e32 v81, v31, v31
	v_mov_b32_e32 v75, v80
	v_mov_b32_e32 v77, v81
	v_pk_add_f32 v[74:75], v[74:75], v[76:77]
	s_add_i32 s8, s8, s55
	v_pk_add_f32 v[76:77], v[72:73], v[74:75]
	ds_read_b128 v[72:75], v88 offset:2576
	s_waitcnt lgkmcnt(1)
	v_pk_fma_f32 v[26:27], v[26:27], v[70:71], v[122:123]
	v_pk_fma_f32 v[24:25], v[24:25], v[68:69], v[120:121]
	v_pk_mul_f32 v[68:69], v[26:27], v[26:27]
	v_pk_mul_f32 v[78:79], v[24:25], v[24:25]
	s_waitcnt lgkmcnt(0)
	v_pk_fma_f32 v[22:23], v[22:23], v[74:75], v[118:119]
	v_pk_mov_b32 v[80:81], v[78:79], v[68:69] op_sel:[1,0]
	v_mov_b32_e32 v79, v69
	ds_read_b128 v[68:71], v88 offset:3072
	v_pk_fma_f32 v[20:21], v[20:21], v[72:73], v[116:117]
	ds_read_b128 v[72:75], v88 offset:3088
	v_pk_add_f32 v[78:79], v[80:81], v[78:79]
	s_cmpk_gt_i32 s8, 0x21ff
	s_waitcnt lgkmcnt(1)
	v_pk_fma_f32 v[16:17], v[16:17], v[68:69], v[112:113]
	v_pk_fma_f32 v[18:19], v[18:19], v[70:71], v[114:115]
	v_mul_f32_e32 v70, v16, v16
	v_pk_add_f32 v[68:69], v[76:77], v[76:77] op_sel:[0,1] op_sel_hi:[1,0]
	v_mul_f32_e32 v80, v17, v17
	v_mov_b32_e32 v69, v70
	v_pk_add_f32 v[70:71], v[78:79], v[78:79] op_sel:[0,1] op_sel_hi:[1,0]
	v_mul_f32_e32 v76, v23, v23
	v_mov_b32_e32 v71, v80
	v_pk_add_f32 v[68:69], v[68:69], v[70:71]
	v_mul_f32_e32 v70, v21, v21
	v_mul_f32_e32 v81, v18, v18
	v_mul_f32_e32 v82, v19, v19
	v_pk_fma_f32 v[70:71], v[20:21], v[20:21], v[70:71] op_sel_hi:[1,1,0]
	v_pk_fma_f32 v[76:77], v[22:23], v[22:23], v[76:77] op_sel_hi:[1,1,0]
	v_mov_b32_e32 v71, v81
	v_mov_b32_e32 v77, v82
	v_pk_add_f32 v[70:71], v[70:71], v[76:77]
	s_waitcnt lgkmcnt(0)
	v_pk_fma_f32 v[14:15], v[14:15], v[74:75], v[110:111]
	v_pk_add_f32 v[76:77], v[68:69], v[70:71]
	v_pk_fma_f32 v[12:13], v[12:13], v[72:73], v[108:109]
	ds_read_b128 v[68:71], v88 offset:3584
	ds_read_b128 v[72:75], v88 offset:3600
	v_pk_mul_f32 v[78:79], v[14:15], v[14:15]
	v_pk_mul_f32 v[80:81], v[12:13], v[12:13]
	s_waitcnt lgkmcnt(1)
	v_pk_fma_f32 v[10:11], v[10:11], v[70:71], v[106:107]
	v_pk_mov_b32 v[82:83], v[80:81], v[78:79] op_sel:[1,0]
	v_mov_b32_e32 v81, v79
	s_waitcnt lgkmcnt(0)
	v_pk_fma_f32 v[4:5], v[4:5], v[72:73], v[100:101]
	v_pk_add_f32 v[78:79], v[82:83], v[80:81]
	v_pk_fma_f32 v[8:9], v[8:9], v[68:69], v[104:105]
	v_mul_f32_e32 v70, v4, v4
	v_pk_add_f32 v[68:69], v[76:77], v[76:77] op_sel:[0,1] op_sel_hi:[1,0]
	v_mul_f32_e32 v72, v5, v5
	v_mov_b32_e32 v69, v70
	v_pk_add_f32 v[70:71], v[78:79], v[78:79] op_sel:[0,1] op_sel_hi:[1,0]
	v_pk_fma_f32 v[6:7], v[6:7], v[74:75], v[102:103]
	v_mov_b32_e32 v71, v72
	v_pk_add_f32 v[68:69], v[68:69], v[70:71]
	v_mul_f32_e32 v70, v9, v9
	v_mul_f32_e32 v73, v6, v6
	v_pk_fma_f32 v[70:71], v[8:9], v[8:9], v[70:71] op_sel_hi:[1,1,0]
	v_mul_f32_e32 v72, v11, v11
	v_mul_f32_e32 v74, v7, v7
	v_mov_b32_e32 v71, v73
	v_pk_fma_f32 v[72:73], v[10:11], v[10:11], v[72:73] op_sel_hi:[1,1,0]
	s_nop 0
	v_mov_b32_e32 v73, v74
	v_pk_add_f32 v[70:71], v[70:71], v[72:73]
	v_bfe_u32 v73, v67, 16, 1
	v_pk_add_f32 v[68:69], v[68:69], v[70:71]
	v_bfe_u32 v70, v61, 16, 1
	v_add_f32_e32 v72, v68, v69
	v_bfe_u32 v68, v62, 16, 1
	v_add3_u32 v68, v62, v68, s6
	v_bfe_u32 v69, v63, 16, 1
	v_lshrrev_b32_e32 v68, 16, v68
	v_add3_u32 v69, v63, v69, s6
	v_and_or_b32 v68, v69, s3, v68
	v_bfe_u32 v69, v60, 16, 1
	v_add3_u32 v69, v60, v69, s6
	v_lshrrev_b32_e32 v69, 16, v69
	v_add3_u32 v70, v61, v70, s6
	v_and_or_b32 v69, v70, s3, v69
	v_bfe_u32 v70, v64, 16, 1
	v_add3_u32 v70, v64, v70, s6
	v_bfe_u32 v71, v65, 16, 1
	v_lshrrev_b32_e32 v70, 16, v70
	v_add3_u32 v71, v65, v71, s6
	v_and_or_b32 v70, v71, s3, v70
	v_bfe_u32 v71, v66, 16, 1
	v_add3_u32 v71, v66, v71, s6
	v_lshrrev_b32_e32 v71, 16, v71
	v_add3_u32 v73, v67, v73, s6
	v_and_or_b32 v71, v73, s3, v71
	global_store_dwordx4 v[174:175], v[68:71], off
	v_bfe_u32 v73, v55, 16, 1
	v_add3_u32 v73, v55, v73, s6
	v_bfe_u32 v68, v56, 16, 1
	v_add3_u32 v68, v56, v68, s6
	v_bfe_u32 v69, v57, 16, 1
	v_lshrrev_b32_e32 v68, 16, v68
	v_add3_u32 v69, v57, v69, s6
	v_and_or_b32 v68, v69, s3, v68
	v_bfe_u32 v69, v58, 16, 1
	v_add3_u32 v69, v58, v69, s6
	v_bfe_u32 v70, v59, 16, 1
	v_lshrrev_b32_e32 v69, 16, v69
	v_add3_u32 v70, v59, v70, s6
	v_and_or_b32 v69, v70, s3, v69
	v_bfe_u32 v70, v52, 16, 1
	v_add3_u32 v70, v52, v70, s6
	v_bfe_u32 v71, v53, 16, 1
	v_lshrrev_b32_e32 v70, 16, v70
	v_add3_u32 v71, v53, v71, s6
	v_and_or_b32 v70, v71, s3, v70
	v_bfe_u32 v71, v54, 16, 1
	v_add3_u32 v71, v54, v71, s6
	v_lshrrev_b32_e32 v71, 16, v71
	v_and_or_b32 v71, v73, s3, v71
	global_store_dwordx4 v[174:175], v[68:71], off offset:256
	v_bfe_u32 v73, v47, 16, 1
	v_add3_u32 v73, v47, v73, s6
	v_bfe_u32 v68, v48, 16, 1
	v_add3_u32 v68, v48, v68, s6
	v_bfe_u32 v69, v49, 16, 1
	v_lshrrev_b32_e32 v68, 16, v68
	v_add3_u32 v69, v49, v69, s6
	v_and_or_b32 v68, v69, s3, v68
	v_bfe_u32 v69, v50, 16, 1
	v_add3_u32 v69, v50, v69, s6
	v_bfe_u32 v70, v51, 16, 1
	v_lshrrev_b32_e32 v69, 16, v69
	v_add3_u32 v70, v51, v70, s6
	v_and_or_b32 v69, v70, s3, v69
	v_bfe_u32 v70, v44, 16, 1
	v_add3_u32 v70, v44, v70, s6
	v_bfe_u32 v71, v45, 16, 1
	v_lshrrev_b32_e32 v70, 16, v70
	v_add3_u32 v71, v45, v71, s6
	v_and_or_b32 v70, v71, s3, v70
	v_bfe_u32 v71, v46, 16, 1
	v_add3_u32 v71, v46, v71, s6
	v_lshrrev_b32_e32 v71, 16, v71
	v_and_or_b32 v71, v73, s3, v71
	global_store_dwordx4 v[174:175], v[68:71], off offset:512
	v_bfe_u32 v73, v39, 16, 1
	v_add3_u32 v73, v39, v73, s6
	v_bfe_u32 v68, v40, 16, 1
	v_add3_u32 v68, v40, v68, s6
	v_bfe_u32 v69, v41, 16, 1
	v_lshrrev_b32_e32 v68, 16, v68
	v_add3_u32 v69, v41, v69, s6
	v_and_or_b32 v68, v69, s3, v68
	v_bfe_u32 v69, v42, 16, 1
	v_add3_u32 v69, v42, v69, s6
	v_bfe_u32 v70, v43, 16, 1
	v_lshrrev_b32_e32 v69, 16, v69
	v_add3_u32 v70, v43, v70, s6
	v_and_or_b32 v69, v70, s3, v69
	v_bfe_u32 v70, v36, 16, 1
	v_add3_u32 v70, v36, v70, s6
	v_bfe_u32 v71, v37, 16, 1
	v_lshrrev_b32_e32 v70, 16, v70
	v_add3_u32 v71, v37, v71, s6
	v_and_or_b32 v70, v71, s3, v70
	v_bfe_u32 v71, v38, 16, 1
	v_add3_u32 v71, v38, v71, s6
	v_lshrrev_b32_e32 v71, 16, v71
	v_and_or_b32 v71, v73, s3, v71
	global_store_dwordx4 v[174:175], v[68:71], off offset:768
	v_bfe_u32 v73, v31, 16, 1
	v_add3_u32 v73, v31, v73, s6
	v_bfe_u32 v68, v32, 16, 1
	v_add3_u32 v68, v32, v68, s6
	v_bfe_u32 v69, v33, 16, 1
	v_lshrrev_b32_e32 v68, 16, v68
	v_add3_u32 v69, v33, v69, s6
	v_and_or_b32 v68, v69, s3, v68
	v_bfe_u32 v69, v34, 16, 1
	v_add3_u32 v69, v34, v69, s6
	v_bfe_u32 v70, v35, 16, 1
	v_lshrrev_b32_e32 v69, 16, v69
	v_add3_u32 v70, v35, v70, s6
	v_and_or_b32 v69, v70, s3, v69
	v_bfe_u32 v70, v28, 16, 1
	v_add3_u32 v70, v28, v70, s6
	v_bfe_u32 v71, v29, 16, 1
	v_lshrrev_b32_e32 v70, 16, v70
	v_add3_u32 v71, v29, v71, s6
	v_and_or_b32 v70, v71, s3, v70
	v_bfe_u32 v71, v30, 16, 1
	v_add3_u32 v71, v30, v71, s6
	v_lshrrev_b32_e32 v71, 16, v71
	v_and_or_b32 v71, v73, s3, v71
	global_store_dwordx4 v[174:175], v[68:71], off offset:1024
	v_bfe_u32 v73, v23, 16, 1
	v_add3_u32 v73, v23, v73, s6
	v_bfe_u32 v68, v24, 16, 1
	v_add3_u32 v68, v24, v68, s6
	v_bfe_u32 v69, v25, 16, 1
	v_lshrrev_b32_e32 v68, 16, v68
	v_add3_u32 v69, v25, v69, s6
	v_and_or_b32 v68, v69, s3, v68
	v_bfe_u32 v69, v26, 16, 1
	v_add3_u32 v69, v26, v69, s6
	v_bfe_u32 v70, v27, 16, 1
	v_lshrrev_b32_e32 v69, 16, v69
	v_add3_u32 v70, v27, v70, s6
	v_and_or_b32 v69, v70, s3, v69
	v_bfe_u32 v70, v20, 16, 1
	v_add3_u32 v70, v20, v70, s6
	v_bfe_u32 v71, v21, 16, 1
	v_lshrrev_b32_e32 v70, 16, v70
	v_add3_u32 v71, v21, v71, s6
	v_and_or_b32 v70, v71, s3, v70
	v_bfe_u32 v71, v22, 16, 1
	v_add3_u32 v71, v22, v71, s6
	v_lshrrev_b32_e32 v71, 16, v71
	v_and_or_b32 v71, v73, s3, v71
	global_store_dwordx4 v[174:175], v[68:71], off offset:1280
	v_bfe_u32 v73, v15, 16, 1
	v_add3_u32 v73, v15, v73, s6
	v_bfe_u32 v68, v16, 16, 1
	v_add3_u32 v68, v16, v68, s6
	v_bfe_u32 v69, v17, 16, 1
	v_lshrrev_b32_e32 v68, 16, v68
	v_add3_u32 v69, v17, v69, s6
	v_and_or_b32 v68, v69, s3, v68
	v_bfe_u32 v69, v18, 16, 1
	v_add3_u32 v69, v18, v69, s6
	v_bfe_u32 v70, v19, 16, 1
	v_lshrrev_b32_e32 v69, 16, v69
	v_add3_u32 v70, v19, v70, s6
	v_and_or_b32 v69, v70, s3, v69
	v_bfe_u32 v70, v12, 16, 1
	v_add3_u32 v70, v12, v70, s6
	v_bfe_u32 v71, v13, 16, 1
	v_lshrrev_b32_e32 v70, 16, v70
	v_add3_u32 v71, v13, v71, s6
	v_and_or_b32 v70, v71, s3, v70
	v_bfe_u32 v71, v14, 16, 1
	v_add3_u32 v71, v14, v71, s6
	v_lshrrev_b32_e32 v71, 16, v71
	v_and_or_b32 v71, v73, s3, v71
	global_store_dwordx4 v[174:175], v[68:71], off offset:1536
	ds_bpermute_b32 v69, v185, v72
	v_bfe_u32 v74, v7, 16, 1
	v_bfe_u32 v68, v8, 16, 1
	v_add3_u32 v68, v8, v68, s6
	v_bfe_u32 v70, v9, 16, 1
	s_waitcnt lgkmcnt(0)
	v_add_f32_e32 v69, v72, v69
	ds_bpermute_b32 v71, v186, v69
	v_lshrrev_b32_e32 v68, 16, v68
	v_add3_u32 v70, v9, v70, s6
	v_and_or_b32 v68, v70, s3, v68
	v_bfe_u32 v70, v10, 16, 1
	s_waitcnt lgkmcnt(0)
	v_add_f32_e32 v71, v69, v71
	ds_bpermute_b32 v73, v187, v71
	v_add3_u32 v70, v10, v70, s6
	v_bfe_u32 v72, v11, 16, 1
	v_lshrrev_b32_e32 v70, 16, v70
	v_add3_u32 v72, v11, v72, s6
	s_waitcnt lgkmcnt(0)
	v_add_f32_e32 v71, v71, v73
	v_and_or_b32 v69, v72, s3, v70
	ds_bpermute_b32 v72, v188, v71
	v_bfe_u32 v70, v4, 16, 1
	v_add3_u32 v70, v4, v70, s6
	v_bfe_u32 v73, v5, 16, 1
	v_lshrrev_b32_e32 v70, 16, v70
	s_waitcnt lgkmcnt(0)
	v_add_f32_e32 v71, v71, v72
	v_fmamk_f32 v71, v71, 0x3a800000, v190
	v_mul_f32_e32 v72, 0x4f800000, v71
	v_cmp_gt_f32_e32 vcc, s7, v71
	v_add3_u32 v73, v5, v73, s6
	v_and_or_b32 v70, v73, s3, v70
	v_cndmask_b32_e32 v71, v71, v72, vcc
	v_sqrt_f32_e32 v72, v71
	v_bfe_u32 v73, v6, 16, 1
	v_add3_u32 v73, v6, v73, s6
	v_lshrrev_b32_e32 v73, 16, v73
	v_add_u32_e32 v75, -1, v72
	v_fma_f32 v76, -v75, v72, v71
	v_cmp_ge_f32_e64 s[4:5], 0, v76
	v_add_u32_e32 v76, 1, v72
	s_nop 0
	v_cndmask_b32_e64 v75, v72, v75, s[4:5]
	v_fma_f32 v72, -v76, v72, v71
	v_cmp_lt_f32_e64 s[4:5], 0, v72
	s_nop 1
	v_cndmask_b32_e64 v72, v75, v76, s[4:5]
	v_mul_f32_e32 v75, 0x37800000, v72
	v_cndmask_b32_e32 v72, v72, v75, vcc
	v_cmp_class_f32_e32 vcc, v71, v191
	s_nop 1
	v_cndmask_b32_e32 v72, v72, v71, vcc
	v_div_scale_f32 v75, s[4:5], v72, v72, 1.0
	v_rcp_f32_e32 v76, v75
	v_add3_u32 v71, v7, v74, s6
	v_and_or_b32 v71, v71, s3, v73
	global_store_dwordx4 v[174:175], v[68:71], off offset:1792
	s_nop 1
	v_fma_f32 v68, -v75, v76, 1.0
	v_fmac_f32_e32 v76, v68, v76
	v_div_scale_f32 v68, vcc, 1.0, v72, 1.0
	v_mul_f32_e32 v69, v68, v76
	v_fma_f32 v70, -v75, v69, v68
	v_fmac_f32_e32 v69, v70, v76
	v_fma_f32 v68, -v75, v69, v68
	v_div_fmas_f32 v68, v68, v76, v69
	v_div_fixup_f32 v68, v68, v72, 1.0
	ds_read_b128 v[70:73], v3 offset:36864
	ds_read_b128 v[74:77], v3
	ds_read_b128 v[78:81], v3 offset:16
	v_pk_mul_f32 v[82:83], v[62:63], v[68:69] op_sel_hi:[1,0]
	v_pk_mul_f32 v[84:85], v[60:61], v[68:69] op_sel_hi:[1,0]
	ds_read_b128 v[60:63], v3 offset:36880
	s_waitcnt lgkmcnt(2)
	v_pk_fma_f32 v[70:71], v[74:75], v[82:83], v[70:71]
	v_pk_mul_f32 v[66:67], v[66:67], v[68:69] op_sel_hi:[1,0]
	v_pk_fma_f32 v[72:73], v[76:77], v[84:85], v[72:73]
	v_pk_mul_f32 v[64:65], v[64:65], v[68:69] op_sel_hi:[1,0]
	s_waitcnt lgkmcnt(0)
	v_pk_fma_f32 v[66:67], v[80:81], v[66:67], v[62:63]
	v_bfe_u32 v62, v70, 16, 1
	v_add3_u32 v62, v70, v62, s6
	v_bfe_u32 v63, v71, 16, 1
	v_lshrrev_b32_e32 v62, 16, v62
	v_add3_u32 v63, v71, v63, s6
	v_and_or_b32 v62, v63, s3, v62
	v_bfe_u32 v63, v72, 16, 1
	v_pk_fma_f32 v[60:61], v[78:79], v[64:65], v[60:61]
	v_add3_u32 v63, v72, v63, s6
	v_bfe_u32 v64, v73, 16, 1
	v_lshrrev_b32_e32 v63, 16, v63
	v_add3_u32 v64, v73, v64, s6
	v_and_or_b32 v63, v64, s3, v63
	v_bfe_u32 v64, v60, 16, 1
	v_add3_u32 v60, v60, v64, s6
	v_bfe_u32 v64, v61, 16, 1
	v_lshrrev_b32_e32 v60, 16, v60
	v_add3_u32 v61, v61, v64, s6
	v_and_or_b32 v64, v61, s3, v60
	v_bfe_u32 v60, v66, 16, 1
	v_add3_u32 v60, v66, v60, s6
	v_bfe_u32 v61, v67, 16, 1
	v_lshrrev_b32_e32 v60, 16, v60
	v_add3_u32 v61, v67, v61, s6
	v_and_or_b32 v65, v61, s3, v60
	v_lshl_add_u64 v[60:61], v[172:173], 1, v[170:171]
	global_store_dwordx4 v[60:61], v[62:65], off
	ds_read_b128 v[62:65], v3 offset:37376
	ds_read_b128 v[70:73], v3 offset:512
	ds_read_b128 v[74:77], v3 offset:528
	v_pk_mul_f32 v[66:67], v[56:57], v[68:69] op_sel_hi:[1,0]
	v_pk_mul_f32 v[78:79], v[58:59], v[68:69] op_sel_hi:[1,0]
	ds_read_b128 v[56:59], v3 offset:37392
	s_waitcnt lgkmcnt(2)
	v_pk_fma_f32 v[62:63], v[70:71], v[66:67], v[62:63]
	v_pk_mul_f32 v[52:53], v[52:53], v[68:69] op_sel_hi:[1,0]
	v_pk_mul_f32 v[54:55], v[54:55], v[68:69] op_sel_hi:[1,0]
	v_pk_fma_f32 v[64:65], v[72:73], v[78:79], v[64:65]
	s_waitcnt lgkmcnt(0)
	v_pk_fma_f32 v[58:59], v[76:77], v[54:55], v[58:59]
	v_pk_fma_f32 v[54:55], v[74:75], v[52:53], v[56:57]
	v_bfe_u32 v52, v62, 16, 1
	v_add3_u32 v52, v62, v52, s6
	v_bfe_u32 v53, v63, 16, 1
	v_lshrrev_b32_e32 v52, 16, v52
	v_add3_u32 v53, v63, v53, s6
	v_and_or_b32 v52, v53, s3, v52
	v_bfe_u32 v53, v64, 16, 1
	v_add3_u32 v53, v64, v53, s6
	v_bfe_u32 v56, v65, 16, 1
	v_lshrrev_b32_e32 v53, 16, v53
	v_add3_u32 v56, v65, v56, s6
	v_and_or_b32 v53, v56, s3, v53
	v_bfe_u32 v56, v54, 16, 1
	v_add3_u32 v54, v54, v56, s6
	v_bfe_u32 v56, v55, 16, 1
	v_lshrrev_b32_e32 v54, 16, v54
	v_add3_u32 v55, v55, v56, s6
	v_and_or_b32 v54, v55, s3, v54
	v_bfe_u32 v55, v58, 16, 1
	v_add3_u32 v55, v58, v55, s6
	v_bfe_u32 v56, v59, 16, 1
	v_lshrrev_b32_e32 v55, 16, v55
	v_add3_u32 v56, v59, v56, s6
	v_and_or_b32 v55, v56, s3, v55
	global_store_dwordx4 v[60:61], v[52:55], off offset:256
	ds_read_b128 v[52:55], v3 offset:37888
	ds_read_b128 v[56:59], v3 offset:1024
	ds_read_b128 v[62:65], v3 offset:1040
	v_pk_mul_f32 v[66:67], v[48:49], v[68:69] op_sel_hi:[1,0]
	v_pk_mul_f32 v[70:71], v[50:51], v[68:69] op_sel_hi:[1,0]
	ds_read_b128 v[48:51], v3 offset:37904
	s_waitcnt lgkmcnt(2)
	v_pk_fma_f32 v[52:53], v[66:67], v[56:57], v[52:53]
	v_pk_mul_f32 v[44:45], v[44:45], v[68:69] op_sel_hi:[1,0]
	v_pk_mul_f32 v[46:47], v[46:47], v[68:69] op_sel_hi:[1,0]
	v_pk_fma_f32 v[54:55], v[70:71], v[58:59], v[54:55]
	s_waitcnt lgkmcnt(0)
	v_pk_fma_f32 v[50:51], v[46:47], v[64:65], v[50:51]
	v_pk_fma_f32 v[46:47], v[44:45], v[62:63], v[48:49]
	v_bfe_u32 v44, v52, 16, 1
	v_add3_u32 v44, v52, v44, s6
	v_bfe_u32 v45, v53, 16, 1
	v_lshrrev_b32_e32 v44, 16, v44
	v_add3_u32 v45, v53, v45, s6
	v_and_or_b32 v44, v45, s3, v44
	v_bfe_u32 v45, v54, 16, 1
	v_add3_u32 v45, v54, v45, s6
	v_bfe_u32 v48, v55, 16, 1
	v_lshrrev_b32_e32 v45, 16, v45
	v_add3_u32 v48, v55, v48, s6
	v_and_or_b32 v45, v48, s3, v45
	v_bfe_u32 v48, v46, 16, 1
	v_add3_u32 v46, v46, v48, s6
	v_bfe_u32 v48, v47, 16, 1
	v_lshrrev_b32_e32 v46, 16, v46
	v_add3_u32 v47, v47, v48, s6
	v_and_or_b32 v46, v47, s3, v46
	v_bfe_u32 v47, v50, 16, 1
	v_add3_u32 v47, v50, v47, s6
	v_bfe_u32 v48, v51, 16, 1
	v_lshrrev_b32_e32 v47, 16, v47
	v_add3_u32 v48, v51, v48, s6
	v_and_or_b32 v47, v48, s3, v47
	global_store_dwordx4 v[60:61], v[44:47], off offset:512
	ds_read_b128 v[44:47], v3 offset:38400
	ds_read_b128 v[48:51], v3 offset:1536
	ds_read_b128 v[52:55], v3 offset:1552
	v_pk_mul_f32 v[56:57], v[40:41], v[68:69] op_sel_hi:[1,0]
	v_pk_mul_f32 v[58:59], v[42:43], v[68:69] op_sel_hi:[1,0]
	ds_read_b128 v[40:43], v3 offset:38416
	s_waitcnt lgkmcnt(2)
	v_pk_fma_f32 v[44:45], v[56:57], v[48:49], v[44:45]
	v_pk_mul_f32 v[36:37], v[36:37], v[68:69] op_sel_hi:[1,0]
	v_pk_mul_f32 v[38:39], v[38:39], v[68:69] op_sel_hi:[1,0]
	v_pk_fma_f32 v[46:47], v[58:59], v[50:51], v[46:47]
	s_waitcnt lgkmcnt(0)
	v_pk_fma_f32 v[42:43], v[38:39], v[54:55], v[42:43]
	v_pk_fma_f32 v[38:39], v[36:37], v[52:53], v[40:41]
	v_bfe_u32 v36, v44, 16, 1
	v_add3_u32 v36, v44, v36, s6
	v_bfe_u32 v37, v45, 16, 1
	v_lshrrev_b32_e32 v36, 16, v36
	v_add3_u32 v37, v45, v37, s6
	v_and_or_b32 v36, v37, s3, v36
	v_bfe_u32 v37, v46, 16, 1
	v_add3_u32 v37, v46, v37, s6
	v_bfe_u32 v40, v47, 16, 1
	v_lshrrev_b32_e32 v37, 16, v37
	v_add3_u32 v40, v47, v40, s6
	v_and_or_b32 v37, v40, s3, v37
	v_bfe_u32 v40, v38, 16, 1
	v_add3_u32 v38, v38, v40, s6
	v_bfe_u32 v40, v39, 16, 1
	v_lshrrev_b32_e32 v38, 16, v38
	v_add3_u32 v39, v39, v40, s6
	v_and_or_b32 v38, v39, s3, v38
	v_bfe_u32 v39, v42, 16, 1
	v_add3_u32 v39, v42, v39, s6
	v_bfe_u32 v40, v43, 16, 1
	v_lshrrev_b32_e32 v39, 16, v39
	v_add3_u32 v40, v43, v40, s6
	v_and_or_b32 v39, v40, s3, v39
	global_store_dwordx4 v[60:61], v[36:39], off offset:768
	ds_read_b128 v[36:39], v3 offset:38912
	ds_read_b128 v[40:43], v3 offset:2048
	ds_read_b128 v[44:47], v3 offset:2064
	v_pk_mul_f32 v[48:49], v[32:33], v[68:69] op_sel_hi:[1,0]
	v_pk_mul_f32 v[50:51], v[34:35], v[68:69] op_sel_hi:[1,0]
	ds_read_b128 v[32:35], v3 offset:38928
	s_waitcnt lgkmcnt(2)
	v_pk_fma_f32 v[36:37], v[48:49], v[40:41], v[36:37]
	v_pk_mul_f32 v[28:29], v[28:29], v[68:69] op_sel_hi:[1,0]
	v_pk_mul_f32 v[30:31], v[30:31], v[68:69] op_sel_hi:[1,0]
	v_pk_fma_f32 v[38:39], v[50:51], v[42:43], v[38:39]
	s_waitcnt lgkmcnt(0)
	v_pk_fma_f32 v[34:35], v[30:31], v[46:47], v[34:35]
	v_pk_fma_f32 v[30:31], v[28:29], v[44:45], v[32:33]
	v_bfe_u32 v28, v36, 16, 1
	v_add3_u32 v28, v36, v28, s6
	v_bfe_u32 v29, v37, 16, 1
	v_lshrrev_b32_e32 v28, 16, v28
	v_add3_u32 v29, v37, v29, s6
	v_and_or_b32 v28, v29, s3, v28
	v_bfe_u32 v29, v38, 16, 1
	v_add3_u32 v29, v38, v29, s6
	v_bfe_u32 v32, v39, 16, 1
	v_lshrrev_b32_e32 v29, 16, v29
	v_add3_u32 v32, v39, v32, s6
	v_and_or_b32 v29, v32, s3, v29
	v_bfe_u32 v32, v30, 16, 1
	v_add3_u32 v30, v30, v32, s6
	v_bfe_u32 v32, v31, 16, 1
	v_lshrrev_b32_e32 v30, 16, v30
	v_add3_u32 v31, v31, v32, s6
	v_and_or_b32 v30, v31, s3, v30
	v_bfe_u32 v31, v34, 16, 1
	v_add3_u32 v31, v34, v31, s6
	v_bfe_u32 v32, v35, 16, 1
	v_lshrrev_b32_e32 v31, 16, v31
	v_add3_u32 v32, v35, v32, s6
	v_and_or_b32 v31, v32, s3, v31
	global_store_dwordx4 v[60:61], v[28:31], off offset:1024
	ds_read_b128 v[28:31], v3 offset:39424
	ds_read_b128 v[32:35], v3 offset:2560
	ds_read_b128 v[36:39], v3 offset:2576
	v_pk_mul_f32 v[40:41], v[24:25], v[68:69] op_sel_hi:[1,0]
	v_pk_mul_f32 v[42:43], v[26:27], v[68:69] op_sel_hi:[1,0]
	ds_read_b128 v[24:27], v3 offset:39440
	s_waitcnt lgkmcnt(2)
	v_pk_fma_f32 v[28:29], v[40:41], v[32:33], v[28:29]
	v_pk_mul_f32 v[20:21], v[20:21], v[68:69] op_sel_hi:[1,0]
	v_pk_mul_f32 v[22:23], v[22:23], v[68:69] op_sel_hi:[1,0]
	v_pk_fma_f32 v[30:31], v[42:43], v[34:35], v[30:31]
	s_waitcnt lgkmcnt(0)
	v_pk_fma_f32 v[26:27], v[22:23], v[38:39], v[26:27]
	v_pk_fma_f32 v[22:23], v[20:21], v[36:37], v[24:25]
	v_bfe_u32 v20, v28, 16, 1
	v_add3_u32 v20, v28, v20, s6
	v_bfe_u32 v21, v29, 16, 1
	v_lshrrev_b32_e32 v20, 16, v20
	v_add3_u32 v21, v29, v21, s6
	v_and_or_b32 v20, v21, s3, v20
	v_bfe_u32 v21, v30, 16, 1
	v_add3_u32 v21, v30, v21, s6
	v_bfe_u32 v24, v31, 16, 1
	v_lshrrev_b32_e32 v21, 16, v21
	v_add3_u32 v24, v31, v24, s6
	v_and_or_b32 v21, v24, s3, v21
	v_bfe_u32 v24, v22, 16, 1
	v_add3_u32 v22, v22, v24, s6
	v_bfe_u32 v24, v23, 16, 1
	v_lshrrev_b32_e32 v22, 16, v22
	v_add3_u32 v23, v23, v24, s6
	v_and_or_b32 v22, v23, s3, v22
	v_bfe_u32 v23, v26, 16, 1
	v_add3_u32 v23, v26, v23, s6
	v_bfe_u32 v24, v27, 16, 1
	v_lshrrev_b32_e32 v23, 16, v23
	v_add3_u32 v24, v27, v24, s6
	v_and_or_b32 v23, v24, s3, v23
	global_store_dwordx4 v[60:61], v[20:23], off offset:1280
	ds_read_b128 v[20:23], v3 offset:39936
	ds_read_b128 v[24:27], v3 offset:3072
	ds_read_b128 v[28:31], v3 offset:3088
	v_pk_mul_f32 v[32:33], v[16:17], v[68:69] op_sel_hi:[1,0]
	v_pk_mul_f32 v[34:35], v[18:19], v[68:69] op_sel_hi:[1,0]
	ds_read_b128 v[16:19], v3 offset:39952
	s_waitcnt lgkmcnt(2)
	v_pk_fma_f32 v[20:21], v[32:33], v[24:25], v[20:21]
	v_pk_mul_f32 v[12:13], v[12:13], v[68:69] op_sel_hi:[1,0]
	v_pk_mul_f32 v[14:15], v[14:15], v[68:69] op_sel_hi:[1,0]
	v_pk_fma_f32 v[22:23], v[34:35], v[26:27], v[22:23]
	s_waitcnt lgkmcnt(0)
	v_pk_fma_f32 v[18:19], v[14:15], v[30:31], v[18:19]
	v_pk_fma_f32 v[14:15], v[12:13], v[28:29], v[16:17]
	v_bfe_u32 v12, v20, 16, 1
	v_add3_u32 v12, v20, v12, s6
	v_bfe_u32 v13, v21, 16, 1
	v_lshrrev_b32_e32 v12, 16, v12
	v_add3_u32 v13, v21, v13, s6
	v_and_or_b32 v12, v13, s3, v12
	v_bfe_u32 v13, v22, 16, 1
	v_add3_u32 v13, v22, v13, s6
	v_bfe_u32 v16, v23, 16, 1
	v_lshrrev_b32_e32 v13, 16, v13
	v_add3_u32 v16, v23, v16, s6
	v_and_or_b32 v13, v16, s3, v13
	v_bfe_u32 v16, v14, 16, 1
	v_add3_u32 v14, v14, v16, s6
	v_bfe_u32 v16, v15, 16, 1
	v_lshrrev_b32_e32 v14, 16, v14
	v_add3_u32 v15, v15, v16, s6
	v_and_or_b32 v14, v15, s3, v14
	v_bfe_u32 v15, v18, 16, 1
	v_add3_u32 v15, v18, v15, s6
	v_bfe_u32 v16, v19, 16, 1
	v_lshrrev_b32_e32 v15, 16, v15
	v_add3_u32 v16, v19, v16, s6
	v_and_or_b32 v15, v16, s3, v15
	global_store_dwordx4 v[60:61], v[12:15], off offset:1536
	ds_read_b128 v[12:15], v3 offset:40448
	ds_read_b128 v[16:19], v3 offset:3584
	ds_read_b128 v[20:23], v3 offset:3600
	v_pk_mul_f32 v[24:25], v[8:9], v[68:69] op_sel_hi:[1,0]
	v_pk_mul_f32 v[26:27], v[10:11], v[68:69] op_sel_hi:[1,0]
	ds_read_b128 v[8:11], v3 offset:40464
	s_waitcnt lgkmcnt(2)
	v_pk_fma_f32 v[12:13], v[24:25], v[16:17], v[12:13]
	v_pk_mul_f32 v[4:5], v[4:5], v[68:69] op_sel_hi:[1,0]
	v_pk_mul_f32 v[6:7], v[6:7], v[68:69] op_sel_hi:[1,0]
	v_bfe_u32 v3, v12, 16, 1
	s_waitcnt lgkmcnt(0)
	v_pk_fma_f32 v[10:11], v[6:7], v[22:23], v[10:11]
	v_pk_fma_f32 v[6:7], v[4:5], v[20:21], v[8:9]
	v_add3_u32 v3, v12, v3, s6
	v_bfe_u32 v4, v13, 16, 1
	v_pk_fma_f32 v[14:15], v[26:27], v[18:19], v[14:15]
	v_lshrrev_b32_e32 v3, 16, v3
	v_add3_u32 v4, v13, v4, s6
	v_and_or_b32 v4, v4, s3, v3
	v_bfe_u32 v3, v14, 16, 1
	v_add3_u32 v3, v14, v3, s6
	v_bfe_u32 v5, v15, 16, 1
	v_lshrrev_b32_e32 v3, 16, v3
	v_add3_u32 v5, v15, v5, s6
	v_and_or_b32 v5, v5, s3, v3
	v_bfe_u32 v3, v6, 16, 1
	v_add3_u32 v3, v6, v3, s6
	v_bfe_u32 v6, v7, 16, 1
	v_lshrrev_b32_e32 v3, 16, v3
	v_add3_u32 v6, v7, v6, s6
	v_and_or_b32 v6, v6, s3, v3
	v_bfe_u32 v3, v10, 16, 1
	v_add3_u32 v3, v10, v3, s6
	v_bfe_u32 v7, v11, 16, 1
	v_lshrrev_b32_e32 v3, 16, v3
	v_add3_u32 v7, v11, v7, s6
	v_and_or_b32 v7, v7, s3, v3
	global_store_dwordx4 v[60:61], v[4:7], off offset:1792
	s_cbranch_scc1 .LBB0_942
.LBB0_934:
	v_lshl_add_u32 v176, s8, 2, v165
	v_lshl_or_b32 v4, v176, 4, v1
	v_ashrrev_i32_e32 v5, 31, v4
	v_lshl_add_u64 v[4:5], v[4:5], 2, s[64:65]
	s_waitcnt vmcnt(8)
	v_mov_b32_e32 v178, v250
	v_cmp_lt_i32_e32 vcc, -1, v178
	v_cndmask_b32_e32 v179, 0, v251, vcc
	s_lshl_b32 s100, s55, 8
	s_mov_b32 s101, 0
	v_lshl_add_u64 v[252:253], v[4:5], 0, s[100:101]
	global_load_dword v250, v[252:253], off
	v_ashrrev_i32_e32 v177, 31, v176
	v_lshlrev_b64 v[4:5], 11, v[176:177]
	v_lshl_add_u64 v[174:175], v[166:167], 0, v[4:5]
	global_load_dwordx4 v[96:99], v[174:175], off
	global_load_dwordx4 v[92:95], v[174:175], off offset:256
	global_load_dwordx4 v[88:91], v[174:175], off offset:512
	global_load_dwordx4 v[80:83], v[174:175], off offset:768
	global_load_dwordx4 v[76:79], v[174:175], off offset:1024
	global_load_dwordx4 v[72:75], v[174:175], off offset:1280
	global_load_dwordx4 v[68:71], v[174:175], off offset:1536
	global_load_dwordx4 v[60:63], v[174:175], off offset:1792
	v_cndmask_b32_e64 v3, 0, 1, vcc
	v_cmp_ne_u32_e32 vcc, 0, v3
	v_lshlrev_b64 v[172:173], 10, v[176:177]
	v_mov_b32_e32 v3, v2
	v_lshrrev_b64 v[4:5], v164, vcc
	v_and_b32_e32 v177, 0xffff, v4
	v_mov_b32_e32 v4, v2
	v_mov_b32_e32 v5, v2
	v_mov_b64_e32 v[162:163], v[4:5]
	v_mov_b64_e32 v[158:159], v[4:5]
	v_mov_b64_e32 v[154:155], v[4:5]
	v_mov_b64_e32 v[150:151], v[4:5]
	v_mov_b64_e32 v[146:147], v[4:5]
	v_mov_b64_e32 v[142:143], v[4:5]
	v_mov_b64_e32 v[138:139], v[4:5]
	v_mov_b64_e32 v[134:135], v[4:5]
	v_mov_b64_e32 v[130:131], v[4:5]
	v_mov_b64_e32 v[126:127], v[4:5]
	v_mov_b64_e32 v[122:123], v[4:5]
	v_mov_b64_e32 v[118:119], v[4:5]
	v_mov_b64_e32 v[114:115], v[4:5]
	v_mov_b64_e32 v[110:111], v[4:5]
	v_mov_b64_e32 v[106:107], v[4:5]
	v_mov_b64_e32 v[102:103], v[4:5]
	v_mov_b64_e32 v[160:161], v[2:3]
	v_mov_b64_e32 v[156:157], v[2:3]
	v_mov_b64_e32 v[152:153], v[2:3]
	v_mov_b64_e32 v[148:149], v[2:3]
	v_mov_b64_e32 v[144:145], v[2:3]
	v_mov_b64_e32 v[140:141], v[2:3]
	v_mov_b64_e32 v[136:137], v[2:3]
	v_mov_b64_e32 v[132:133], v[2:3]
	v_mov_b64_e32 v[128:129], v[2:3]
	v_mov_b64_e32 v[124:125], v[2:3]
	v_mov_b64_e32 v[120:121], v[2:3]
	v_mov_b64_e32 v[116:117], v[2:3]
	v_mov_b64_e32 v[112:113], v[2:3]
	v_mov_b64_e32 v[108:109], v[2:3]
	v_mov_b64_e32 v[104:105], v[2:3]
	v_mov_b64_e32 v[100:101], v[2:3]
	s_branch .LBB0_938

.LBB0_938:
	v_mov_b64_e32 v[84:85], v[100:101]
	v_mov_b64_e32 v[64:65], v[104:105]
	v_mov_b64_e32 v[56:57], v[108:109]
	v_mov_b64_e32 v[52:53], v[112:113]
	v_mov_b64_e32 v[48:49], v[116:117]
	v_mov_b64_e32 v[44:45], v[120:121]
	v_mov_b64_e32 v[40:41], v[124:125]
	v_mov_b64_e32 v[36:37], v[128:129]
	v_mov_b64_e32 v[32:33], v[132:133]
	v_mov_b64_e32 v[28:29], v[136:137]
	v_mov_b64_e32 v[24:25], v[140:141]
	v_mov_b64_e32 v[20:21], v[144:145]
	v_mov_b64_e32 v[16:17], v[148:149]
	v_mov_b64_e32 v[12:13], v[152:153]
	v_mov_b64_e32 v[8:9], v[156:157]
	v_mov_b64_e32 v[4:5], v[160:161]
	v_mov_b64_e32 v[86:87], v[102:103]
	v_mov_b64_e32 v[66:67], v[106:107]
	v_mov_b64_e32 v[58:59], v[110:111]
	v_mov_b64_e32 v[54:55], v[114:115]
	v_mov_b64_e32 v[50:51], v[118:119]
	v_mov_b64_e32 v[46:47], v[122:123]
	v_mov_b64_e32 v[42:43], v[126:127]
	v_mov_b64_e32 v[38:39], v[130:131]
	v_mov_b64_e32 v[34:35], v[134:135]
	v_mov_b64_e32 v[30:31], v[138:139]
	v_mov_b64_e32 v[26:27], v[142:143]
	v_mov_b64_e32 v[22:23], v[146:147]
	v_mov_b64_e32 v[18:19], v[150:151]
	v_mov_b64_e32 v[14:15], v[154:155]
	v_mov_b64_e32 v[10:11], v[158:159]
	v_mov_b64_e32 v[6:7], v[162:163]
	v_cmp_ne_u32_e32 vcc, 0, v177
	s_cbranch_vccz .LBB0_941
	v_ffbl_b32_e32 v3, v177
	v_cndmask_b32_e32 v3, 0, v3, vcc
	v_add_u32_e32 v3, v3, v164
	v_and_or_b32 v3, v3, 63, v184
	v_lshlrev_b32_e32 v3, 2, v3
	s_waitcnt lgkmcnt(1)
	ds_bpermute_b32 v182, v3, v178
	s_waitcnt lgkmcnt(1)
	ds_bpermute_b32 v180, v3, v179
	v_mov_b64_e32 v[102:103], v[86:87]
	v_mov_b64_e32 v[106:107], v[66:67]
	v_mov_b64_e32 v[110:111], v[58:59]
	v_mov_b64_e32 v[114:115], v[54:55]
	v_mov_b64_e32 v[118:119], v[50:51]
	v_mov_b64_e32 v[122:123], v[46:47]
	v_mov_b64_e32 v[126:127], v[42:43]
	v_mov_b64_e32 v[130:131], v[38:39]
	v_mov_b64_e32 v[134:135], v[34:35]
	v_mov_b64_e32 v[138:139], v[30:31]
	v_mov_b64_e32 v[142:143], v[26:27]
	v_mov_b64_e32 v[146:147], v[22:23]
	v_mov_b64_e32 v[150:151], v[18:19]
	v_mov_b64_e32 v[154:155], v[14:15]
	v_mov_b64_e32 v[158:159], v[10:11]
	v_mov_b64_e32 v[162:163], v[6:7]
	v_mov_b64_e32 v[100:101], v[84:85]
	v_mov_b64_e32 v[104:105], v[64:65]
	v_mov_b64_e32 v[108:109], v[56:57]
	v_mov_b64_e32 v[112:113], v[52:53]
	v_mov_b64_e32 v[116:117], v[48:49]
	v_mov_b64_e32 v[120:121], v[44:45]
	v_mov_b64_e32 v[124:125], v[40:41]
	v_mov_b64_e32 v[128:129], v[36:37]
	v_mov_b64_e32 v[132:133], v[32:33]
	v_mov_b64_e32 v[136:137], v[28:29]
	v_mov_b64_e32 v[140:141], v[24:25]
	v_mov_b64_e32 v[144:145], v[20:21]
	v_mov_b64_e32 v[148:149], v[16:17]
	v_mov_b64_e32 v[152:153], v[12:13]
	v_mov_b64_e32 v[156:157], v[8:9]
	v_mov_b64_e32 v[160:161], v[4:5]
	s_and_saveexec_b64 s[4:5], vcc
	s_xor_b64 s[4:5], exec, s[4:5]
	s_cbranch_execz .LBB0_937
	s_waitcnt lgkmcnt(1)
	v_ashrrev_i32_e32 v183, 31, v182
	v_lshlrev_b64 v[100:101], 10, v[182:183]
	v_lshl_add_u64 v[100:101], v[168:169], 0, v[100:101]
	global_load_dwordx2 v[102:103], v[100:101], off
	global_load_dwordx2 v[104:105], v[100:101], off offset:128
	global_load_dwordx2 v[106:107], v[100:101], off offset:256
	global_load_dwordx2 v[108:109], v[100:101], off offset:384
	global_load_dwordx2 v[110:111], v[100:101], off offset:512
	global_load_dwordx2 v[112:113], v[100:101], off offset:640
	global_load_dwordx2 v[114:115], v[100:101], off offset:768
	s_nop 0
	global_load_dwordx2 v[100:101], v[100:101], off offset:896
	s_waitcnt vmcnt(7)
	v_cvt_pk_f32_fp8_e32 v[116:117], v102
	v_cvt_pk_f32_fp8_sdwa v[118:119], v102 src0_sel:WORD_1
	v_cvt_pk_f32_fp8_e32 v[120:121], v103
	v_cvt_pk_f32_fp8_sdwa v[122:123], v103 src0_sel:WORD_1
	s_waitcnt vmcnt(6)
	v_cvt_pk_f32_fp8_e32 v[124:125], v104
	v_cvt_pk_f32_fp8_sdwa v[126:127], v104 src0_sel:WORD_1
	v_cvt_pk_f32_fp8_e32 v[128:129], v105
	v_cvt_pk_f32_fp8_sdwa v[130:131], v105 src0_sel:WORD_1
	s_waitcnt vmcnt(5)
	v_cvt_pk_f32_fp8_e32 v[132:133], v106
	v_cvt_pk_f32_fp8_sdwa v[134:135], v106 src0_sel:WORD_1
	v_cvt_pk_f32_fp8_e32 v[136:137], v107
	v_cvt_pk_f32_fp8_sdwa v[138:139], v107 src0_sel:WORD_1
	s_waitcnt vmcnt(4)
	v_cvt_pk_f32_fp8_e32 v[140:141], v108
	v_cvt_pk_f32_fp8_sdwa v[142:143], v108 src0_sel:WORD_1
	v_cvt_pk_f32_fp8_e32 v[144:145], v109
	v_cvt_pk_f32_fp8_sdwa v[146:147], v109 src0_sel:WORD_1
	s_waitcnt vmcnt(3)
	v_cvt_pk_f32_fp8_e32 v[148:149], v110
	v_cvt_pk_f32_fp8_sdwa v[150:151], v110 src0_sel:WORD_1
	v_cvt_pk_f32_fp8_e32 v[152:153], v111
	v_cvt_pk_f32_fp8_sdwa v[154:155], v111 src0_sel:WORD_1
	s_waitcnt vmcnt(2)
	v_cvt_pk_f32_fp8_e32 v[156:157], v112
	v_cvt_pk_f32_fp8_sdwa v[158:159], v112 src0_sel:WORD_1
	v_cvt_pk_f32_fp8_e32 v[160:161], v113
	v_cvt_pk_f32_fp8_sdwa v[162:163], v113 src0_sel:WORD_1
	s_waitcnt vmcnt(1)
	v_cvt_pk_f32_fp8_e32 v[182:183], v114
	v_cvt_pk_f32_fp8_sdwa v[192:193], v114 src0_sel:WORD_1
	v_cvt_pk_f32_fp8_e32 v[194:195], v115
	v_cvt_pk_f32_fp8_sdwa v[196:197], v115 src0_sel:WORD_1
	s_waitcnt vmcnt(0)
	v_cvt_pk_f32_fp8_e32 v[198:199], v100
	v_cvt_pk_f32_fp8_sdwa v[200:201], v100 src0_sel:WORD_1
	v_cvt_pk_f32_fp8_e32 v[202:203], v101
	v_cvt_pk_f32_fp8_sdwa v[204:205], v101 src0_sel:WORD_1
	s_waitcnt lgkmcnt(0)
	v_pk_fma_f32 v[102:103], v[180:181], v[118:119], v[86:87] op_sel_hi:[0,1,1]
	v_pk_fma_f32 v[100:101], v[180:181], v[116:117], v[84:85] op_sel_hi:[0,1,1]
	v_pk_fma_f32 v[106:107], v[180:181], v[122:123], v[66:67] op_sel_hi:[0,1,1]
	v_pk_fma_f32 v[104:105], v[180:181], v[120:121], v[64:65] op_sel_hi:[0,1,1]
	v_pk_fma_f32 v[110:111], v[180:181], v[126:127], v[58:59] op_sel_hi:[0,1,1]
	v_pk_fma_f32 v[108:109], v[180:181], v[124:125], v[56:57] op_sel_hi:[0,1,1]
	v_pk_fma_f32 v[114:115], v[180:181], v[130:131], v[54:55] op_sel_hi:[0,1,1]
	v_pk_fma_f32 v[112:113], v[180:181], v[128:129], v[52:53] op_sel_hi:[0,1,1]
	v_pk_fma_f32 v[118:119], v[180:181], v[134:135], v[50:51] op_sel_hi:[0,1,1]
	v_pk_fma_f32 v[116:117], v[180:181], v[132:133], v[48:49] op_sel_hi:[0,1,1]
	v_pk_fma_f32 v[122:123], v[180:181], v[138:139], v[46:47] op_sel_hi:[0,1,1]
	v_pk_fma_f32 v[120:121], v[180:181], v[136:137], v[44:45] op_sel_hi:[0,1,1]
	v_pk_fma_f32 v[126:127], v[180:181], v[142:143], v[42:43] op_sel_hi:[0,1,1]
	v_pk_fma_f32 v[124:125], v[180:181], v[140:141], v[40:41] op_sel_hi:[0,1,1]
	v_pk_fma_f32 v[130:131], v[180:181], v[146:147], v[38:39] op_sel_hi:[0,1,1]
	v_pk_fma_f32 v[128:129], v[180:181], v[144:145], v[36:37] op_sel_hi:[0,1,1]
	v_pk_fma_f32 v[134:135], v[180:181], v[150:151], v[34:35] op_sel_hi:[0,1,1]
	v_pk_fma_f32 v[132:133], v[180:181], v[148:149], v[32:33] op_sel_hi:[0,1,1]
	v_pk_fma_f32 v[138:139], v[180:181], v[154:155], v[30:31] op_sel_hi:[0,1,1]
	v_pk_fma_f32 v[136:137], v[180:181], v[152:153], v[28:29] op_sel_hi:[0,1,1]
	v_pk_fma_f32 v[142:143], v[180:181], v[158:159], v[26:27] op_sel_hi:[0,1,1]
	v_pk_fma_f32 v[140:141], v[180:181], v[156:157], v[24:25] op_sel_hi:[0,1,1]
	v_pk_fma_f32 v[146:147], v[180:181], v[162:163], v[22:23] op_sel_hi:[0,1,1]
	v_pk_fma_f32 v[144:145], v[180:181], v[160:161], v[20:21] op_sel_hi:[0,1,1]
	v_pk_fma_f32 v[150:151], v[180:181], v[192:193], v[18:19] op_sel_hi:[0,1,1]
	v_pk_fma_f32 v[148:149], v[180:181], v[182:183], v[16:17] op_sel_hi:[0,1,1]
	v_pk_fma_f32 v[154:155], v[180:181], v[196:197], v[14:15] op_sel_hi:[0,1,1]
	v_pk_fma_f32 v[152:153], v[180:181], v[194:195], v[12:13] op_sel_hi:[0,1,1]
	v_pk_fma_f32 v[158:159], v[180:181], v[200:201], v[10:11] op_sel_hi:[0,1,1]
	v_pk_fma_f32 v[156:157], v[180:181], v[198:199], v[8:9] op_sel_hi:[0,1,1]
	v_pk_fma_f32 v[162:163], v[180:181], v[204:205], v[6:7] op_sel_hi:[0,1,1]
	v_pk_fma_f32 v[160:161], v[180:181], v[202:203], v[4:5] op_sel_hi:[0,1,1]
	s_branch .LBB0_937

.LBB0_2600:
	s_or_b64 exec, exec, s[4:5]
	v_and_b32_e32 v2, 63, v0
	s_cmpk_lt_i32 s54, 0x2000
	s_waitcnt lgkmcnt(0)
	s_barrier
	s_cbranch_scc0 .LBB0_2611
	v_and_b32_e32 v1, 15, v2
	v_ashrrev_i32_e32 v165, 4, v2
	v_and_b32_e32 v164, -16, v2
	v_mov_b32_e32 v2, 0
	v_lshlrev_b32_e32 v6, 3, v1
	v_mov_b32_e32 v7, v2
	v_lshl_add_u64 v[168:169], s[68:69], 0, v[6:7]
	v_mbcnt_lo_u32_b32 v6, -1, 0
	v_mbcnt_hi_u32_b32 v6, -1, v6
	v_and_b32_e32 v184, 64, v6
	v_xor_b32_e32 v7, 1, v6
	v_add_u32_e32 v8, 64, v184
	v_cmp_lt_i32_e32 vcc, v7, v8
	v_readlane_b32 s4, v255, 8
	v_lshlrev_b32_e32 v3, 5, v1
	v_cndmask_b32_e32 v7, v6, v7, vcc
	v_lshlrev_b32_e32 v185, 2, v7
	v_xor_b32_e32 v7, 2, v6
	v_cmp_lt_i32_e32 vcc, v7, v8
	v_lshlrev_b32_e32 v4, 4, v1
	v_mov_b32_e32 v5, v2
	v_cndmask_b32_e32 v7, v6, v7, vcc
	v_lshlrev_b32_e32 v186, 2, v7
	v_xor_b32_e32 v7, 4, v6
	v_cmp_lt_i32_e32 vcc, v7, v8
	v_readlane_b32 s5, v255, 9
	v_add_u32_e32 v181, s3, v3
	v_cndmask_b32_e32 v7, v6, v7, vcc
	v_lshlrev_b32_e32 v187, 2, v7
	v_xor_b32_e32 v7, 8, v6
	v_cmp_lt_i32_e32 vcc, v7, v8
	v_lshl_add_u64 v[166:167], s[66:67], 0, v[4:5]
	v_add_u32_e32 v189, 0, v3
	v_cndmask_b32_e32 v6, v6, v7, vcc
	v_lshlrev_b32_e32 v188, 2, v6
	v_lshl_add_u64 v[170:171], s[4:5], 0, v[4:5]
	s_mov_b32 s3, 0xffff0000
	s_movk_i32 s6, 0x7fff
	v_mov_b32_e32 v190, 0x358637bd
	s_mov_b32 s7, 0xf800000
	v_mov_b32_e32 v191, 0x260
	s_mov_b32 s8, s54
	v_lshl_add_u32 v252, s8, 2, v165
	v_lshl_or_b32 v252, v252, 4, v1
	v_ashrrev_i32_e32 v253, 31, v252
	v_lshl_add_u64 v[252:253], v[252:253], 2, s[64:65]
	global_load_dword v250, v[252:253], off
	s_waitcnt vmcnt(0)
	v_max_i32_e32 v252, 0, v250
	v_min_u32_e32 v252, 0x10fff, v252
	v_mov_b32_e32 v253, 0
	v_lshl_add_u64 v[252:253], v[252:253], 2, s[62:63]
	global_load_dword v251, v[252:253], off
	s_waitcnt vmcnt(0)
	s_branch .LBB0_2603
.LBB0_2602:
	v_min_i32_e32 v3, 0x8000, v176
	v_and_b32_e32 v3, 0xfffff000, v3
	s_waitcnt vmcnt(5)
	v_lshlrev_b32_e32 v148, 16, v88
	v_and_b32_e32 v149, 0xffff0000, v88
	v_add_u32_e32 v88, v181, v3
	s_waitcnt vmcnt(1)
	v_lshlrev_b32_e32 v112, 16, v68
	v_lshlrev_b32_e32 v114, 16, v69
	v_lshlrev_b32_e32 v108, 16, v70
	v_lshlrev_b32_e32 v110, 16, v71
	v_and_b32_e32 v113, 0xffff0000, v68
	v_and_b32_e32 v115, 0xffff0000, v69
	v_and_b32_e32 v109, 0xffff0000, v70
	v_and_b32_e32 v111, 0xffff0000, v71
	ds_read_b128 v[68:71], v88
	v_lshlrev_b32_e32 v120, 16, v72
	v_lshlrev_b32_e32 v122, 16, v73
	v_lshlrev_b32_e32 v116, 16, v74
	v_lshlrev_b32_e32 v118, 16, v75
	v_and_b32_e32 v121, 0xffff0000, v72
	v_and_b32_e32 v123, 0xffff0000, v73
	v_and_b32_e32 v117, 0xffff0000, v74
	v_and_b32_e32 v119, 0xffff0000, v75
	ds_read_b128 v[72:75], v88 offset:16
	v_lshlrev_b32_e32 v132, 16, v96
	v_lshlrev_b32_e32 v134, 16, v97
	v_and_b32_e32 v133, 0xffff0000, v96
	v_and_b32_e32 v135, 0xffff0000, v97
	s_waitcnt vmcnt(0)
	v_max_i32_e32 v252, 0, v250
	v_min_u32_e32 v252, 0x10fff, v252
	v_mov_b32_e32 v253, 0
	v_lshl_add_u64 v[252:253], v[252:253], 2, s[62:63]
	global_load_dword v251, v[252:253], off
	v_lshlrev_b32_e32 v104, 16, v60
	v_lshlrev_b32_e32 v106, 16, v61
	v_lshlrev_b32_e32 v100, 16, v62
	v_lshlrev_b32_e32 v102, 16, v63
	v_and_b32_e32 v105, 0xffff0000, v60
	v_and_b32_e32 v107, 0xffff0000, v61
	v_and_b32_e32 v101, 0xffff0000, v62
	v_and_b32_e32 v103, 0xffff0000, v63
	s_waitcnt lgkmcnt(1)
	v_pk_fma_f32 v[60:61], v[86:87], v[70:71], v[134:135]
	v_pk_fma_f32 v[62:63], v[84:85], v[68:69], v[132:133]
	v_pk_mul_f32 v[68:69], v[60:61], v[60:61]
	v_pk_mul_f32 v[70:71], v[62:63], v[62:63]
	v_lshlrev_b32_e32 v136, 16, v98
	v_lshlrev_b32_e32 v138, 16, v99
	v_lshlrev_b32_e32 v128, 16, v76
	v_lshlrev_b32_e32 v130, 16, v77
	v_and_b32_e32 v137, 0xffff0000, v98
	v_and_b32_e32 v139, 0xffff0000, v99
	v_and_b32_e32 v129, 0xffff0000, v76
	v_and_b32_e32 v131, 0xffff0000, v77
	v_pk_mov_b32 v[76:77], v[70:71], v[68:69] op_sel:[1,0]
	v_mov_b32_e32 v71, v69
	v_pk_add_f32 v[76:77], v[76:77], v[70:71]
	s_waitcnt lgkmcnt(0)
	v_pk_fma_f32 v[66:67], v[66:67], v[74:75], v[138:139]
	v_pk_fma_f32 v[64:65], v[64:65], v[72:73], v[136:137]
	ds_read_b128 v[68:71], v88 offset:512
	ds_read_b128 v[72:75], v88 offset:528
	v_lshlrev_b32_e32 v144, 16, v94
	v_lshlrev_b32_e32 v156, 16, v80
	v_lshlrev_b32_e32 v158, 16, v81
	v_lshlrev_b32_e32 v124, 16, v78
	v_lshlrev_b32_e32 v126, 16, v79
	v_and_b32_e32 v145, 0xffff0000, v94
	v_and_b32_e32 v157, 0xffff0000, v80
	v_and_b32_e32 v159, 0xffff0000, v81
	v_and_b32_e32 v125, 0xffff0000, v78
	v_and_b32_e32 v127, 0xffff0000, v79
	v_pk_mul_f32 v[78:79], v[66:67], v[66:67]
	v_pk_mul_f32 v[80:81], v[64:65], v[64:65]
	v_lshlrev_b32_e32 v140, 16, v92
	v_lshlrev_b32_e32 v142, 16, v93
	v_lshlrev_b32_e32 v160, 16, v82
	v_lshlrev_b32_e32 v162, 16, v83
	v_and_b32_e32 v141, 0xffff0000, v92
	v_and_b32_e32 v143, 0xffff0000, v93
	v_and_b32_e32 v161, 0xffff0000, v82
	v_and_b32_e32 v163, 0xffff0000, v83
	v_pk_mov_b32 v[82:83], v[80:81], v[78:79] op_sel:[1,0]
	v_mov_b32_e32 v81, v79
	s_waitcnt lgkmcnt(0)
	v_pk_fma_f32 v[52:53], v[52:53], v[72:73], v[144:145]
	v_pk_add_f32 v[78:79], v[82:83], v[80:81]
	v_pk_fma_f32 v[58:59], v[58:59], v[70:71], v[142:143]
	v_pk_fma_f32 v[56:57], v[56:57], v[68:69], v[140:141]
	v_mul_f32_e32 v70, v52, v52
	v_pk_add_f32 v[68:69], v[76:77], v[76:77] op_sel:[0,1] op_sel_hi:[1,0]
	v_mul_f32_e32 v72, v53, v53
	v_mov_b32_e32 v69, v70
	v_pk_add_f32 v[70:71], v[78:79], v[78:79] op_sel:[0,1] op_sel_hi:[1,0]
	v_lshlrev_b32_e32 v146, 16, v95
	v_mov_b32_e32 v71, v72
	v_and_b32_e32 v147, 0xffff0000, v95
	v_pk_add_f32 v[72:73], v[68:69], v[70:71]
	v_mul_f32_e32 v68, v57, v57
	v_pk_fma_f32 v[54:55], v[54:55], v[74:75], v[146:147]
	v_pk_fma_f32 v[74:75], v[56:57], v[56:57], v[68:69] op_sel_hi:[1,1,0]
	v_mul_f32_e32 v68, v59, v59
	v_pk_fma_f32 v[76:77], v[58:59], v[58:59], v[68:69] op_sel_hi:[1,1,0]
	ds_read_b128 v[68:71], v88 offset:1024
	v_mul_f32_e32 v80, v54, v54
	v_mul_f32_e32 v81, v55, v55
	v_mov_b32_e32 v75, v80
	v_mov_b32_e32 v77, v81
	v_lshlrev_b32_e32 v150, 16, v89
	v_and_b32_e32 v151, 0xffff0000, v89
	v_pk_add_f32 v[74:75], v[74:75], v[76:77]
	v_lshlrev_b32_e32 v152, 16, v90
	v_pk_add_f32 v[76:77], v[72:73], v[74:75]
	ds_read_b128 v[72:75], v88 offset:1040
	s_waitcnt lgkmcnt(1)
	v_pk_fma_f32 v[50:51], v[50:51], v[70:71], v[150:151]
	v_pk_fma_f32 v[48:49], v[48:49], v[68:69], v[148:149]
	v_pk_mul_f32 v[68:69], v[50:51], v[50:51]
	v_pk_mul_f32 v[78:79], v[48:49], v[48:49]
	v_lshlrev_b32_e32 v154, 16, v91
	v_pk_mov_b32 v[80:81], v[78:79], v[68:69] op_sel:[1,0]
	v_mov_b32_e32 v79, v69
	ds_read_b128 v[68:71], v88 offset:1536
	v_and_b32_e32 v153, 0xffff0000, v90
	v_and_b32_e32 v155, 0xffff0000, v91
	s_waitcnt lgkmcnt(1)
	v_pk_fma_f32 v[46:47], v[46:47], v[74:75], v[154:155]
	v_pk_fma_f32 v[44:45], v[44:45], v[72:73], v[152:153]
	ds_read_b128 v[72:75], v88 offset:1552
	s_waitcnt lgkmcnt(1)
	v_pk_fma_f32 v[40:41], v[40:41], v[68:69], v[156:157]
	v_pk_add_f32 v[78:79], v[80:81], v[78:79]
	v_pk_fma_f32 v[42:43], v[42:43], v[70:71], v[158:159]
	v_mul_f32_e32 v70, v40, v40
	v_pk_add_f32 v[68:69], v[76:77], v[76:77] op_sel:[0,1] op_sel_hi:[1,0]
	v_mul_f32_e32 v80, v41, v41
	v_mov_b32_e32 v69, v70
	v_pk_add_f32 v[70:71], v[78:79], v[78:79] op_sel:[0,1] op_sel_hi:[1,0]
	v_mul_f32_e32 v76, v47, v47
	v_mov_b32_e32 v71, v80
	v_pk_add_f32 v[68:69], v[68:69], v[70:71]
	v_mul_f32_e32 v70, v45, v45
	v_mul_f32_e32 v81, v42, v42
	v_mul_f32_e32 v82, v43, v43
	v_pk_fma_f32 v[70:71], v[44:45], v[44:45], v[70:71] op_sel_hi:[1,1,0]
	v_pk_fma_f32 v[76:77], v[46:47], v[46:47], v[76:77] op_sel_hi:[1,1,0]
	v_mov_b32_e32 v71, v81
	v_mov_b32_e32 v77, v82
	v_pk_add_f32 v[70:71], v[70:71], v[76:77]
	s_waitcnt lgkmcnt(0)
	v_pk_fma_f32 v[38:39], v[38:39], v[74:75], v[162:163]
	v_pk_add_f32 v[76:77], v[68:69], v[70:71]
	v_pk_fma_f32 v[36:37], v[36:37], v[72:73], v[160:161]
	ds_read_b128 v[68:71], v88 offset:2048
	ds_read_b128 v[72:75], v88 offset:2064
	v_pk_mul_f32 v[78:79], v[38:39], v[38:39]
	v_pk_mul_f32 v[80:81], v[36:37], v[36:37]
	v_add_u32_e32 v3, v189, v3
	v_pk_mov_b32 v[82:83], v[80:81], v[78:79] op_sel:[1,0]
	v_mov_b32_e32 v81, v79
	s_waitcnt lgkmcnt(0)
	v_pk_fma_f32 v[28:29], v[28:29], v[72:73], v[124:125]
	v_pk_add_f32 v[78:79], v[82:83], v[80:81]
	v_pk_fma_f32 v[34:35], v[34:35], v[70:71], v[130:131]
	v_pk_fma_f32 v[32:33], v[32:33], v[68:69], v[128:129]
	v_mul_f32_e32 v70, v28, v28
	v_pk_add_f32 v[68:69], v[76:77], v[76:77] op_sel:[0,1] op_sel_hi:[1,0]
	v_mul_f32_e32 v72, v29, v29
	v_mov_b32_e32 v69, v70
	v_pk_add_f32 v[70:71], v[78:79], v[78:79] op_sel:[0,1] op_sel_hi:[1,0]
	v_pk_fma_f32 v[30:31], v[30:31], v[74:75], v[126:127]
	v_mov_b32_e32 v71, v72
	v_pk_add_f32 v[72:73], v[68:69], v[70:71]
	v_mul_f32_e32 v68, v33, v33
	v_pk_fma_f32 v[74:75], v[32:33], v[32:33], v[68:69] op_sel_hi:[1,1,0]
	v_mul_f32_e32 v68, v35, v35
	v_pk_fma_f32 v[76:77], v[34:35], v[34:35], v[68:69] op_sel_hi:[1,1,0]
	ds_read_b128 v[68:71], v88 offset:2560
	v_mul_f32_e32 v80, v30, v30
	v_mul_f32_e32 v81, v31, v31
	v_mov_b32_e32 v75, v80
	v_mov_b32_e32 v77, v81
	v_pk_add_f32 v[74:75], v[74:75], v[76:77]
	s_add_i32 s8, s8, s55
	v_pk_add_f32 v[76:77], v[72:73], v[74:75]
	ds_read_b128 v[72:75], v88 offset:2576
	s_waitcnt lgkmcnt(1)
	v_pk_fma_f32 v[26:27], v[26:27], v[70:71], v[122:123]
	v_pk_fma_f32 v[24:25], v[24:25], v[68:69], v[120:121]
	v_pk_mul_f32 v[68:69], v[26:27], v[26:27]
	v_pk_mul_f32 v[78:79], v[24:25], v[24:25]
	s_waitcnt lgkmcnt(0)
	v_pk_fma_f32 v[22:23], v[22:23], v[74:75], v[118:119]
	v_pk_mov_b32 v[80:81], v[78:79], v[68:69] op_sel:[1,0]
	v_mov_b32_e32 v79, v69
	ds_read_b128 v[68:71], v88 offset:3072
	v_pk_fma_f32 v[20:21], v[20:21], v[72:73], v[116:117]
	ds_read_b128 v[72:75], v88 offset:3088
	v_pk_add_f32 v[78:79], v[80:81], v[78:79]
	s_cmpk_gt_i32 s8, 0x1fff
	s_waitcnt lgkmcnt(1)
	v_pk_fma_f32 v[16:17], v[16:17], v[68:69], v[112:113]
	v_pk_fma_f32 v[18:19], v[18:19], v[70:71], v[114:115]
	v_mul_f32_e32 v70, v16, v16
	v_pk_add_f32 v[68:69], v[76:77], v[76:77] op_sel:[0,1] op_sel_hi:[1,0]
	v_mul_f32_e32 v80, v17, v17
	v_mov_b32_e32 v69, v70
	v_pk_add_f32 v[70:71], v[78:79], v[78:79] op_sel:[0,1] op_sel_hi:[1,0]
	v_mul_f32_e32 v76, v23, v23
	v_mov_b32_e32 v71, v80
	v_pk_add_f32 v[68:69], v[68:69], v[70:71]
	v_mul_f32_e32 v70, v21, v21
	v_mul_f32_e32 v81, v18, v18
	v_mul_f32_e32 v82, v19, v19
	v_pk_fma_f32 v[70:71], v[20:21], v[20:21], v[70:71] op_sel_hi:[1,1,0]
	v_pk_fma_f32 v[76:77], v[22:23], v[22:23], v[76:77] op_sel_hi:[1,1,0]
	v_mov_b32_e32 v71, v81
	v_mov_b32_e32 v77, v82
	v_pk_add_f32 v[70:71], v[70:71], v[76:77]
	s_waitcnt lgkmcnt(0)
	v_pk_fma_f32 v[14:15], v[14:15], v[74:75], v[110:111]
	v_pk_add_f32 v[76:77], v[68:69], v[70:71]
	v_pk_fma_f32 v[12:13], v[12:13], v[72:73], v[108:109]
	ds_read_b128 v[68:71], v88 offset:3584
	ds_read_b128 v[72:75], v88 offset:3600
	v_pk_mul_f32 v[78:79], v[14:15], v[14:15]
	v_pk_mul_f32 v[80:81], v[12:13], v[12:13]
	s_waitcnt lgkmcnt(1)
	v_pk_fma_f32 v[10:11], v[10:11], v[70:71], v[106:107]
	v_pk_mov_b32 v[82:83], v[80:81], v[78:79] op_sel:[1,0]
	v_mov_b32_e32 v81, v79
	s_waitcnt lgkmcnt(0)
	v_pk_fma_f32 v[4:5], v[4:5], v[72:73], v[100:101]
	v_pk_add_f32 v[78:79], v[82:83], v[80:81]
	v_pk_fma_f32 v[8:9], v[8:9], v[68:69], v[104:105]
	v_mul_f32_e32 v70, v4, v4
	v_pk_add_f32 v[68:69], v[76:77], v[76:77] op_sel:[0,1] op_sel_hi:[1,0]
	v_mul_f32_e32 v72, v5, v5
	v_mov_b32_e32 v69, v70
	v_pk_add_f32 v[70:71], v[78:79], v[78:79] op_sel:[0,1] op_sel_hi:[1,0]
	v_pk_fma_f32 v[6:7], v[6:7], v[74:75], v[102:103]
	v_mov_b32_e32 v71, v72
	v_pk_add_f32 v[68:69], v[68:69], v[70:71]
	v_mul_f32_e32 v70, v9, v9
	v_mul_f32_e32 v73, v6, v6
	v_pk_fma_f32 v[70:71], v[8:9], v[8:9], v[70:71] op_sel_hi:[1,1,0]
	v_mul_f32_e32 v72, v11, v11
	v_mul_f32_e32 v74, v7, v7
	v_mov_b32_e32 v71, v73
	v_pk_fma_f32 v[72:73], v[10:11], v[10:11], v[72:73] op_sel_hi:[1,1,0]
	s_nop 0
	v_mov_b32_e32 v73, v74
	v_pk_add_f32 v[70:71], v[70:71], v[72:73]
	v_bfe_u32 v73, v67, 16, 1
	v_pk_add_f32 v[68:69], v[68:69], v[70:71]
	v_bfe_u32 v70, v61, 16, 1
	v_add_f32_e32 v72, v68, v69
	v_bfe_u32 v68, v62, 16, 1
	v_add3_u32 v68, v62, v68, s6
	v_bfe_u32 v69, v63, 16, 1
	v_lshrrev_b32_e32 v68, 16, v68
	v_add3_u32 v69, v63, v69, s6
	v_and_or_b32 v68, v69, s3, v68
	v_bfe_u32 v69, v60, 16, 1
	v_add3_u32 v69, v60, v69, s6
	v_lshrrev_b32_e32 v69, 16, v69
	v_add3_u32 v70, v61, v70, s6
	v_and_or_b32 v69, v70, s3, v69
	v_bfe_u32 v70, v64, 16, 1
	v_add3_u32 v70, v64, v70, s6
	v_bfe_u32 v71, v65, 16, 1
	v_lshrrev_b32_e32 v70, 16, v70
	v_add3_u32 v71, v65, v71, s6
	v_and_or_b32 v70, v71, s3, v70
	v_bfe_u32 v71, v66, 16, 1
	v_add3_u32 v71, v66, v71, s6
	v_lshrrev_b32_e32 v71, 16, v71
	v_add3_u32 v73, v67, v73, s6
	v_and_or_b32 v71, v73, s3, v71
	global_store_dwordx4 v[174:175], v[68:71], off
	v_bfe_u32 v73, v55, 16, 1
	v_add3_u32 v73, v55, v73, s6
	v_bfe_u32 v68, v56, 16, 1
	v_add3_u32 v68, v56, v68, s6
	v_bfe_u32 v69, v57, 16, 1
	v_lshrrev_b32_e32 v68, 16, v68
	v_add3_u32 v69, v57, v69, s6
	v_and_or_b32 v68, v69, s3, v68
	v_bfe_u32 v69, v58, 16, 1
	v_add3_u32 v69, v58, v69, s6
	v_bfe_u32 v70, v59, 16, 1
	v_lshrrev_b32_e32 v69, 16, v69
	v_add3_u32 v70, v59, v70, s6
	v_and_or_b32 v69, v70, s3, v69
	v_bfe_u32 v70, v52, 16, 1
	v_add3_u32 v70, v52, v70, s6
	v_bfe_u32 v71, v53, 16, 1
	v_lshrrev_b32_e32 v70, 16, v70
	v_add3_u32 v71, v53, v71, s6
	v_and_or_b32 v70, v71, s3, v70
	v_bfe_u32 v71, v54, 16, 1
	v_add3_u32 v71, v54, v71, s6
	v_lshrrev_b32_e32 v71, 16, v71
	v_and_or_b32 v71, v73, s3, v71
	global_store_dwordx4 v[174:175], v[68:71], off offset:256
	v_bfe_u32 v73, v47, 16, 1
	v_add3_u32 v73, v47, v73, s6
	v_bfe_u32 v68, v48, 16, 1
	v_add3_u32 v68, v48, v68, s6
	v_bfe_u32 v69, v49, 16, 1
	v_lshrrev_b32_e32 v68, 16, v68
	v_add3_u32 v69, v49, v69, s6
	v_and_or_b32 v68, v69, s3, v68
	v_bfe_u32 v69, v50, 16, 1
	v_add3_u32 v69, v50, v69, s6
	v_bfe_u32 v70, v51, 16, 1
	v_lshrrev_b32_e32 v69, 16, v69
	v_add3_u32 v70, v51, v70, s6
	v_and_or_b32 v69, v70, s3, v69
	v_bfe_u32 v70, v44, 16, 1
	v_add3_u32 v70, v44, v70, s6
	v_bfe_u32 v71, v45, 16, 1
	v_lshrrev_b32_e32 v70, 16, v70
	v_add3_u32 v71, v45, v71, s6
	v_and_or_b32 v70, v71, s3, v70
	v_bfe_u32 v71, v46, 16, 1
	v_add3_u32 v71, v46, v71, s6
	v_lshrrev_b32_e32 v71, 16, v71
	v_and_or_b32 v71, v73, s3, v71
	global_store_dwordx4 v[174:175], v[68:71], off offset:512
	v_bfe_u32 v73, v39, 16, 1
	v_add3_u32 v73, v39, v73, s6
	v_bfe_u32 v68, v40, 16, 1
	v_add3_u32 v68, v40, v68, s6
	v_bfe_u32 v69, v41, 16, 1
	v_lshrrev_b32_e32 v68, 16, v68
	v_add3_u32 v69, v41, v69, s6
	v_and_or_b32 v68, v69, s3, v68
	v_bfe_u32 v69, v42, 16, 1
	v_add3_u32 v69, v42, v69, s6
	v_bfe_u32 v70, v43, 16, 1
	v_lshrrev_b32_e32 v69, 16, v69
	v_add3_u32 v70, v43, v70, s6
	v_and_or_b32 v69, v70, s3, v69
	v_bfe_u32 v70, v36, 16, 1
	v_add3_u32 v70, v36, v70, s6
	v_bfe_u32 v71, v37, 16, 1
	v_lshrrev_b32_e32 v70, 16, v70
	v_add3_u32 v71, v37, v71, s6
	v_and_or_b32 v70, v71, s3, v70
	v_bfe_u32 v71, v38, 16, 1
	v_add3_u32 v71, v38, v71, s6
	v_lshrrev_b32_e32 v71, 16, v71
	v_and_or_b32 v71, v73, s3, v71
	global_store_dwordx4 v[174:175], v[68:71], off offset:768
	v_bfe_u32 v73, v31, 16, 1
	v_add3_u32 v73, v31, v73, s6
	v_bfe_u32 v68, v32, 16, 1
	v_add3_u32 v68, v32, v68, s6
	v_bfe_u32 v69, v33, 16, 1
	v_lshrrev_b32_e32 v68, 16, v68
	v_add3_u32 v69, v33, v69, s6
	v_and_or_b32 v68, v69, s3, v68
	v_bfe_u32 v69, v34, 16, 1
	v_add3_u32 v69, v34, v69, s6
	v_bfe_u32 v70, v35, 16, 1
	v_lshrrev_b32_e32 v69, 16, v69
	v_add3_u32 v70, v35, v70, s6
	v_and_or_b32 v69, v70, s3, v69
	v_bfe_u32 v70, v28, 16, 1
	v_add3_u32 v70, v28, v70, s6
	v_bfe_u32 v71, v29, 16, 1
	v_lshrrev_b32_e32 v70, 16, v70
	v_add3_u32 v71, v29, v71, s6
	v_and_or_b32 v70, v71, s3, v70
	v_bfe_u32 v71, v30, 16, 1
	v_add3_u32 v71, v30, v71, s6
	v_lshrrev_b32_e32 v71, 16, v71
	v_and_or_b32 v71, v73, s3, v71
	global_store_dwordx4 v[174:175], v[68:71], off offset:1024
	v_bfe_u32 v73, v23, 16, 1
	v_add3_u32 v73, v23, v73, s6
	v_bfe_u32 v68, v24, 16, 1
	v_add3_u32 v68, v24, v68, s6
	v_bfe_u32 v69, v25, 16, 1
	v_lshrrev_b32_e32 v68, 16, v68
	v_add3_u32 v69, v25, v69, s6
	v_and_or_b32 v68, v69, s3, v68
	v_bfe_u32 v69, v26, 16, 1
	v_add3_u32 v69, v26, v69, s6
	v_bfe_u32 v70, v27, 16, 1
	v_lshrrev_b32_e32 v69, 16, v69
	v_add3_u32 v70, v27, v70, s6
	v_and_or_b32 v69, v70, s3, v69
	v_bfe_u32 v70, v20, 16, 1
	v_add3_u32 v70, v20, v70, s6
	v_bfe_u32 v71, v21, 16, 1
	v_lshrrev_b32_e32 v70, 16, v70
	v_add3_u32 v71, v21, v71, s6
	v_and_or_b32 v70, v71, s3, v70
	v_bfe_u32 v71, v22, 16, 1
	v_add3_u32 v71, v22, v71, s6
	v_lshrrev_b32_e32 v71, 16, v71
	v_and_or_b32 v71, v73, s3, v71
	global_store_dwordx4 v[174:175], v[68:71], off offset:1280
	v_bfe_u32 v73, v15, 16, 1
	v_add3_u32 v73, v15, v73, s6
	v_bfe_u32 v68, v16, 16, 1
	v_add3_u32 v68, v16, v68, s6
	v_bfe_u32 v69, v17, 16, 1
	v_lshrrev_b32_e32 v68, 16, v68
	v_add3_u32 v69, v17, v69, s6
	v_and_or_b32 v68, v69, s3, v68
	v_bfe_u32 v69, v18, 16, 1
	v_add3_u32 v69, v18, v69, s6
	v_bfe_u32 v70, v19, 16, 1
	v_lshrrev_b32_e32 v69, 16, v69
	v_add3_u32 v70, v19, v70, s6
	v_and_or_b32 v69, v70, s3, v69
	v_bfe_u32 v70, v12, 16, 1
	v_add3_u32 v70, v12, v70, s6
	v_bfe_u32 v71, v13, 16, 1
	v_lshrrev_b32_e32 v70, 16, v70
	v_add3_u32 v71, v13, v71, s6
	v_and_or_b32 v70, v71, s3, v70
	v_bfe_u32 v71, v14, 16, 1
	v_add3_u32 v71, v14, v71, s6
	v_lshrrev_b32_e32 v71, 16, v71
	v_and_or_b32 v71, v73, s3, v71
	global_store_dwordx4 v[174:175], v[68:71], off offset:1536
	ds_bpermute_b32 v69, v185, v72
	v_bfe_u32 v74, v7, 16, 1
	v_bfe_u32 v68, v8, 16, 1
	v_add3_u32 v68, v8, v68, s6
	v_bfe_u32 v70, v9, 16, 1
	s_waitcnt lgkmcnt(0)
	v_add_f32_e32 v69, v72, v69
	ds_bpermute_b32 v71, v186, v69
	v_lshrrev_b32_e32 v68, 16, v68
	v_add3_u32 v70, v9, v70, s6
	v_and_or_b32 v68, v70, s3, v68
	v_bfe_u32 v70, v10, 16, 1
	s_waitcnt lgkmcnt(0)
	v_add_f32_e32 v71, v69, v71
	ds_bpermute_b32 v73, v187, v71
	v_add3_u32 v70, v10, v70, s6
	v_bfe_u32 v72, v11, 16, 1
	v_lshrrev_b32_e32 v70, 16, v70
	v_add3_u32 v72, v11, v72, s6
	s_waitcnt lgkmcnt(0)
	v_add_f32_e32 v71, v71, v73
	v_and_or_b32 v69, v72, s3, v70
	ds_bpermute_b32 v72, v188, v71
	v_bfe_u32 v70, v4, 16, 1
	v_add3_u32 v70, v4, v70, s6
	v_bfe_u32 v73, v5, 16, 1
	v_lshrrev_b32_e32 v70, 16, v70
	s_waitcnt lgkmcnt(0)
	v_add_f32_e32 v71, v71, v72
	v_fmamk_f32 v71, v71, 0x3a800000, v190
	v_mul_f32_e32 v72, 0x4f800000, v71
	v_cmp_gt_f32_e32 vcc, s7, v71
	v_add3_u32 v73, v5, v73, s6
	v_and_or_b32 v70, v73, s3, v70
	v_cndmask_b32_e32 v71, v71, v72, vcc
	v_sqrt_f32_e32 v72, v71
	v_bfe_u32 v73, v6, 16, 1
	v_add3_u32 v73, v6, v73, s6
	v_lshrrev_b32_e32 v73, 16, v73
	v_add_u32_e32 v75, -1, v72
	v_fma_f32 v76, -v75, v72, v71
	v_cmp_ge_f32_e64 s[4:5], 0, v76
	v_add_u32_e32 v76, 1, v72
	s_nop 0
	v_cndmask_b32_e64 v75, v72, v75, s[4:5]
	v_fma_f32 v72, -v76, v72, v71
	v_cmp_lt_f32_e64 s[4:5], 0, v72
	s_nop 1
	v_cndmask_b32_e64 v72, v75, v76, s[4:5]
	v_mul_f32_e32 v75, 0x37800000, v72
	v_cndmask_b32_e32 v72, v72, v75, vcc
	v_cmp_class_f32_e32 vcc, v71, v191
	s_nop 1
	v_cndmask_b32_e32 v72, v72, v71, vcc
	v_div_scale_f32 v75, s[4:5], v72, v72, 1.0
	v_rcp_f32_e32 v76, v75
	v_add3_u32 v71, v7, v74, s6
	v_and_or_b32 v71, v71, s3, v73
	global_store_dwordx4 v[174:175], v[68:71], off offset:1792
	s_nop 1
	v_fma_f32 v68, -v75, v76, 1.0
	v_fmac_f32_e32 v76, v68, v76
	v_div_scale_f32 v68, vcc, 1.0, v72, 1.0
	v_mul_f32_e32 v69, v68, v76
	v_fma_f32 v70, -v75, v69, v68
	v_fmac_f32_e32 v69, v70, v76
	v_fma_f32 v68, -v75, v69, v68
	v_div_fmas_f32 v68, v68, v76, v69
	v_div_fixup_f32 v68, v68, v72, 1.0
	ds_read_b128 v[70:73], v3 offset:36864
	ds_read_b128 v[74:77], v3
	ds_read_b128 v[78:81], v3 offset:16
	v_pk_mul_f32 v[82:83], v[62:63], v[68:69] op_sel_hi:[1,0]
	v_pk_mul_f32 v[84:85], v[60:61], v[68:69] op_sel_hi:[1,0]
	ds_read_b128 v[60:63], v3 offset:36880
	s_waitcnt lgkmcnt(2)
	v_pk_fma_f32 v[70:71], v[74:75], v[82:83], v[70:71]
	v_pk_mul_f32 v[66:67], v[66:67], v[68:69] op_sel_hi:[1,0]
	v_pk_fma_f32 v[72:73], v[76:77], v[84:85], v[72:73]
	v_pk_mul_f32 v[64:65], v[64:65], v[68:69] op_sel_hi:[1,0]
	s_waitcnt lgkmcnt(0)
	v_pk_fma_f32 v[66:67], v[80:81], v[66:67], v[62:63]
	v_bfe_u32 v62, v70, 16, 1
	v_add3_u32 v62, v70, v62, s6
	v_bfe_u32 v63, v71, 16, 1
	v_lshrrev_b32_e32 v62, 16, v62
	v_add3_u32 v63, v71, v63, s6
	v_and_or_b32 v62, v63, s3, v62
	v_bfe_u32 v63, v72, 16, 1
	v_pk_fma_f32 v[60:61], v[78:79], v[64:65], v[60:61]
	v_add3_u32 v63, v72, v63, s6
	v_bfe_u32 v64, v73, 16, 1
	v_lshrrev_b32_e32 v63, 16, v63
	v_add3_u32 v64, v73, v64, s6
	v_and_or_b32 v63, v64, s3, v63
	v_bfe_u32 v64, v60, 16, 1
	v_add3_u32 v60, v60, v64, s6
	v_bfe_u32 v64, v61, 16, 1
	v_lshrrev_b32_e32 v60, 16, v60
	v_add3_u32 v61, v61, v64, s6
	v_and_or_b32 v64, v61, s3, v60
	v_bfe_u32 v60, v66, 16, 1
	v_add3_u32 v60, v66, v60, s6
	v_bfe_u32 v61, v67, 16, 1
	v_lshrrev_b32_e32 v60, 16, v60
	v_add3_u32 v61, v67, v61, s6
	v_and_or_b32 v65, v61, s3, v60
	v_lshl_add_u64 v[60:61], v[172:173], 1, v[170:171]
	global_store_dwordx4 v[60:61], v[62:65], off
	ds_read_b128 v[62:65], v3 offset:37376
	ds_read_b128 v[70:73], v3 offset:512
	ds_read_b128 v[74:77], v3 offset:528
	v_pk_mul_f32 v[66:67], v[56:57], v[68:69] op_sel_hi:[1,0]
	v_pk_mul_f32 v[78:79], v[58:59], v[68:69] op_sel_hi:[1,0]
	ds_read_b128 v[56:59], v3 offset:37392
	s_waitcnt lgkmcnt(2)
	v_pk_fma_f32 v[62:63], v[70:71], v[66:67], v[62:63]
	v_pk_mul_f32 v[52:53], v[52:53], v[68:69] op_sel_hi:[1,0]
	v_pk_mul_f32 v[54:55], v[54:55], v[68:69] op_sel_hi:[1,0]
	v_pk_fma_f32 v[64:65], v[72:73], v[78:79], v[64:65]
	s_waitcnt lgkmcnt(0)
	v_pk_fma_f32 v[58:59], v[76:77], v[54:55], v[58:59]
	v_pk_fma_f32 v[54:55], v[74:75], v[52:53], v[56:57]
	v_bfe_u32 v52, v62, 16, 1
	v_add3_u32 v52, v62, v52, s6
	v_bfe_u32 v53, v63, 16, 1
	v_lshrrev_b32_e32 v52, 16, v52
	v_add3_u32 v53, v63, v53, s6
	v_and_or_b32 v52, v53, s3, v52
	v_bfe_u32 v53, v64, 16, 1
	v_add3_u32 v53, v64, v53, s6
	v_bfe_u32 v56, v65, 16, 1
	v_lshrrev_b32_e32 v53, 16, v53
	v_add3_u32 v56, v65, v56, s6
	v_and_or_b32 v53, v56, s3, v53
	v_bfe_u32 v56, v54, 16, 1
	v_add3_u32 v54, v54, v56, s6
	v_bfe_u32 v56, v55, 16, 1
	v_lshrrev_b32_e32 v54, 16, v54
	v_add3_u32 v55, v55, v56, s6
	v_and_or_b32 v54, v55, s3, v54
	v_bfe_u32 v55, v58, 16, 1
	v_add3_u32 v55, v58, v55, s6
	v_bfe_u32 v56, v59, 16, 1
	v_lshrrev_b32_e32 v55, 16, v55
	v_add3_u32 v56, v59, v56, s6
	v_and_or_b32 v55, v56, s3, v55
	global_store_dwordx4 v[60:61], v[52:55], off offset:256
	ds_read_b128 v[52:55], v3 offset:37888
	ds_read_b128 v[56:59], v3 offset:1024
	ds_read_b128 v[62:65], v3 offset:1040
	v_pk_mul_f32 v[66:67], v[48:49], v[68:69] op_sel_hi:[1,0]
	v_pk_mul_f32 v[70:71], v[50:51], v[68:69] op_sel_hi:[1,0]
	ds_read_b128 v[48:51], v3 offset:37904
	s_waitcnt lgkmcnt(2)
	v_pk_fma_f32 v[52:53], v[66:67], v[56:57], v[52:53]
	v_pk_mul_f32 v[44:45], v[44:45], v[68:69] op_sel_hi:[1,0]
	v_pk_mul_f32 v[46:47], v[46:47], v[68:69] op_sel_hi:[1,0]
	v_pk_fma_f32 v[54:55], v[70:71], v[58:59], v[54:55]
	s_waitcnt lgkmcnt(0)
	v_pk_fma_f32 v[50:51], v[46:47], v[64:65], v[50:51]
	v_pk_fma_f32 v[46:47], v[44:45], v[62:63], v[48:49]
	v_bfe_u32 v44, v52, 16, 1
	v_add3_u32 v44, v52, v44, s6
	v_bfe_u32 v45, v53, 16, 1
	v_lshrrev_b32_e32 v44, 16, v44
	v_add3_u32 v45, v53, v45, s6
	v_and_or_b32 v44, v45, s3, v44
	v_bfe_u32 v45, v54, 16, 1
	v_add3_u32 v45, v54, v45, s6
	v_bfe_u32 v48, v55, 16, 1
	v_lshrrev_b32_e32 v45, 16, v45
	v_add3_u32 v48, v55, v48, s6
	v_and_or_b32 v45, v48, s3, v45
	v_bfe_u32 v48, v46, 16, 1
	v_add3_u32 v46, v46, v48, s6
	v_bfe_u32 v48, v47, 16, 1
	v_lshrrev_b32_e32 v46, 16, v46
	v_add3_u32 v47, v47, v48, s6
	v_and_or_b32 v46, v47, s3, v46
	v_bfe_u32 v47, v50, 16, 1
	v_add3_u32 v47, v50, v47, s6
	v_bfe_u32 v48, v51, 16, 1
	v_lshrrev_b32_e32 v47, 16, v47
	v_add3_u32 v48, v51, v48, s6
	v_and_or_b32 v47, v48, s3, v47
	global_store_dwordx4 v[60:61], v[44:47], off offset:512
	ds_read_b128 v[44:47], v3 offset:38400
	ds_read_b128 v[48:51], v3 offset:1536
	ds_read_b128 v[52:55], v3 offset:1552
	v_pk_mul_f32 v[56:57], v[40:41], v[68:69] op_sel_hi:[1,0]
	v_pk_mul_f32 v[58:59], v[42:43], v[68:69] op_sel_hi:[1,0]
	ds_read_b128 v[40:43], v3 offset:38416
	s_waitcnt lgkmcnt(2)
	v_pk_fma_f32 v[44:45], v[56:57], v[48:49], v[44:45]
	v_pk_mul_f32 v[36:37], v[36:37], v[68:69] op_sel_hi:[1,0]
	v_pk_mul_f32 v[38:39], v[38:39], v[68:69] op_sel_hi:[1,0]
	v_pk_fma_f32 v[46:47], v[58:59], v[50:51], v[46:47]
	s_waitcnt lgkmcnt(0)
	v_pk_fma_f32 v[42:43], v[38:39], v[54:55], v[42:43]
	v_pk_fma_f32 v[38:39], v[36:37], v[52:53], v[40:41]
	v_bfe_u32 v36, v44, 16, 1
	v_add3_u32 v36, v44, v36, s6
	v_bfe_u32 v37, v45, 16, 1
	v_lshrrev_b32_e32 v36, 16, v36
	v_add3_u32 v37, v45, v37, s6
	v_and_or_b32 v36, v37, s3, v36
	v_bfe_u32 v37, v46, 16, 1
	v_add3_u32 v37, v46, v37, s6
	v_bfe_u32 v40, v47, 16, 1
	v_lshrrev_b32_e32 v37, 16, v37
	v_add3_u32 v40, v47, v40, s6
	v_and_or_b32 v37, v40, s3, v37
	v_bfe_u32 v40, v38, 16, 1
	v_add3_u32 v38, v38, v40, s6
	v_bfe_u32 v40, v39, 16, 1
	v_lshrrev_b32_e32 v38, 16, v38
	v_add3_u32 v39, v39, v40, s6
	v_and_or_b32 v38, v39, s3, v38
	v_bfe_u32 v39, v42, 16, 1
	v_add3_u32 v39, v42, v39, s6
	v_bfe_u32 v40, v43, 16, 1
	v_lshrrev_b32_e32 v39, 16, v39
	v_add3_u32 v40, v43, v40, s6
	v_and_or_b32 v39, v40, s3, v39
	global_store_dwordx4 v[60:61], v[36:39], off offset:768
	ds_read_b128 v[36:39], v3 offset:38912
	ds_read_b128 v[40:43], v3 offset:2048
	ds_read_b128 v[44:47], v3 offset:2064
	v_pk_mul_f32 v[48:49], v[32:33], v[68:69] op_sel_hi:[1,0]
	v_pk_mul_f32 v[50:51], v[34:35], v[68:69] op_sel_hi:[1,0]
	ds_read_b128 v[32:35], v3 offset:38928
	s_waitcnt lgkmcnt(2)
	v_pk_fma_f32 v[36:37], v[48:49], v[40:41], v[36:37]
	v_pk_mul_f32 v[28:29], v[28:29], v[68:69] op_sel_hi:[1,0]
	v_pk_mul_f32 v[30:31], v[30:31], v[68:69] op_sel_hi:[1,0]
	v_pk_fma_f32 v[38:39], v[50:51], v[42:43], v[38:39]
	s_waitcnt lgkmcnt(0)
	v_pk_fma_f32 v[34:35], v[30:31], v[46:47], v[34:35]
	v_pk_fma_f32 v[30:31], v[28:29], v[44:45], v[32:33]
	v_bfe_u32 v28, v36, 16, 1
	v_add3_u32 v28, v36, v28, s6
	v_bfe_u32 v29, v37, 16, 1
	v_lshrrev_b32_e32 v28, 16, v28
	v_add3_u32 v29, v37, v29, s6
	v_and_or_b32 v28, v29, s3, v28
	v_bfe_u32 v29, v38, 16, 1
	v_add3_u32 v29, v38, v29, s6
	v_bfe_u32 v32, v39, 16, 1
	v_lshrrev_b32_e32 v29, 16, v29
	v_add3_u32 v32, v39, v32, s6
	v_and_or_b32 v29, v32, s3, v29
	v_bfe_u32 v32, v30, 16, 1
	v_add3_u32 v30, v30, v32, s6
	v_bfe_u32 v32, v31, 16, 1
	v_lshrrev_b32_e32 v30, 16, v30
	v_add3_u32 v31, v31, v32, s6
	v_and_or_b32 v30, v31, s3, v30
	v_bfe_u32 v31, v34, 16, 1
	v_add3_u32 v31, v34, v31, s6
	v_bfe_u32 v32, v35, 16, 1
	v_lshrrev_b32_e32 v31, 16, v31
	v_add3_u32 v32, v35, v32, s6
	v_and_or_b32 v31, v32, s3, v31
	global_store_dwordx4 v[60:61], v[28:31], off offset:1024
	ds_read_b128 v[28:31], v3 offset:39424
	ds_read_b128 v[32:35], v3 offset:2560
	ds_read_b128 v[36:39], v3 offset:2576
	v_pk_mul_f32 v[40:41], v[24:25], v[68:69] op_sel_hi:[1,0]
	v_pk_mul_f32 v[42:43], v[26:27], v[68:69] op_sel_hi:[1,0]
	ds_read_b128 v[24:27], v3 offset:39440
	s_waitcnt lgkmcnt(2)
	v_pk_fma_f32 v[28:29], v[40:41], v[32:33], v[28:29]
	v_pk_mul_f32 v[20:21], v[20:21], v[68:69] op_sel_hi:[1,0]
	v_pk_mul_f32 v[22:23], v[22:23], v[68:69] op_sel_hi:[1,0]
	v_pk_fma_f32 v[30:31], v[42:43], v[34:35], v[30:31]
	s_waitcnt lgkmcnt(0)
	v_pk_fma_f32 v[26:27], v[22:23], v[38:39], v[26:27]
	v_pk_fma_f32 v[22:23], v[20:21], v[36:37], v[24:25]
	v_bfe_u32 v20, v28, 16, 1
	v_add3_u32 v20, v28, v20, s6
	v_bfe_u32 v21, v29, 16, 1
	v_lshrrev_b32_e32 v20, 16, v20
	v_add3_u32 v21, v29, v21, s6
	v_and_or_b32 v20, v21, s3, v20
	v_bfe_u32 v21, v30, 16, 1
	v_add3_u32 v21, v30, v21, s6
	v_bfe_u32 v24, v31, 16, 1
	v_lshrrev_b32_e32 v21, 16, v21
	v_add3_u32 v24, v31, v24, s6
	v_and_or_b32 v21, v24, s3, v21
	v_bfe_u32 v24, v22, 16, 1
	v_add3_u32 v22, v22, v24, s6
	v_bfe_u32 v24, v23, 16, 1
	v_lshrrev_b32_e32 v22, 16, v22
	v_add3_u32 v23, v23, v24, s6
	v_and_or_b32 v22, v23, s3, v22
	v_bfe_u32 v23, v26, 16, 1
	v_add3_u32 v23, v26, v23, s6
	v_bfe_u32 v24, v27, 16, 1
	v_lshrrev_b32_e32 v23, 16, v23
	v_add3_u32 v24, v27, v24, s6
	v_and_or_b32 v23, v24, s3, v23
	global_store_dwordx4 v[60:61], v[20:23], off offset:1280
	ds_read_b128 v[20:23], v3 offset:39936
	ds_read_b128 v[24:27], v3 offset:3072
	ds_read_b128 v[28:31], v3 offset:3088
	v_pk_mul_f32 v[32:33], v[16:17], v[68:69] op_sel_hi:[1,0]
	v_pk_mul_f32 v[34:35], v[18:19], v[68:69] op_sel_hi:[1,0]
	ds_read_b128 v[16:19], v3 offset:39952
	s_waitcnt lgkmcnt(2)
	v_pk_fma_f32 v[20:21], v[32:33], v[24:25], v[20:21]
	v_pk_mul_f32 v[12:13], v[12:13], v[68:69] op_sel_hi:[1,0]
	v_pk_mul_f32 v[14:15], v[14:15], v[68:69] op_sel_hi:[1,0]
	v_pk_fma_f32 v[22:23], v[34:35], v[26:27], v[22:23]
	s_waitcnt lgkmcnt(0)
	v_pk_fma_f32 v[18:19], v[14:15], v[30:31], v[18:19]
	v_pk_fma_f32 v[14:15], v[12:13], v[28:29], v[16:17]
	v_bfe_u32 v12, v20, 16, 1
	v_add3_u32 v12, v20, v12, s6
	v_bfe_u32 v13, v21, 16, 1
	v_lshrrev_b32_e32 v12, 16, v12
	v_add3_u32 v13, v21, v13, s6
	v_and_or_b32 v12, v13, s3, v12
	v_bfe_u32 v13, v22, 16, 1
	v_add3_u32 v13, v22, v13, s6
	v_bfe_u32 v16, v23, 16, 1
	v_lshrrev_b32_e32 v13, 16, v13
	v_add3_u32 v16, v23, v16, s6
	v_and_or_b32 v13, v16, s3, v13
	v_bfe_u32 v16, v14, 16, 1
	v_add3_u32 v14, v14, v16, s6
	v_bfe_u32 v16, v15, 16, 1
	v_lshrrev_b32_e32 v14, 16, v14
	v_add3_u32 v15, v15, v16, s6
	v_and_or_b32 v14, v15, s3, v14
	v_bfe_u32 v15, v18, 16, 1
	v_add3_u32 v15, v18, v15, s6
	v_bfe_u32 v16, v19, 16, 1
	v_lshrrev_b32_e32 v15, 16, v15
	v_add3_u32 v16, v19, v16, s6
	v_and_or_b32 v15, v16, s3, v15
	global_store_dwordx4 v[60:61], v[12:15], off offset:1536
	ds_read_b128 v[12:15], v3 offset:40448
	ds_read_b128 v[16:19], v3 offset:3584
	ds_read_b128 v[20:23], v3 offset:3600
	v_pk_mul_f32 v[24:25], v[8:9], v[68:69] op_sel_hi:[1,0]
	v_pk_mul_f32 v[26:27], v[10:11], v[68:69] op_sel_hi:[1,0]
	ds_read_b128 v[8:11], v3 offset:40464
	s_waitcnt lgkmcnt(2)
	v_pk_fma_f32 v[12:13], v[24:25], v[16:17], v[12:13]
	v_pk_mul_f32 v[4:5], v[4:5], v[68:69] op_sel_hi:[1,0]
	v_pk_mul_f32 v[6:7], v[6:7], v[68:69] op_sel_hi:[1,0]
	v_bfe_u32 v3, v12, 16, 1
	s_waitcnt lgkmcnt(0)
	v_pk_fma_f32 v[10:11], v[6:7], v[22:23], v[10:11]
	v_pk_fma_f32 v[6:7], v[4:5], v[20:21], v[8:9]
	v_add3_u32 v3, v12, v3, s6
	v_bfe_u32 v4, v13, 16, 1
	v_pk_fma_f32 v[14:15], v[26:27], v[18:19], v[14:15]
	v_lshrrev_b32_e32 v3, 16, v3
	v_add3_u32 v4, v13, v4, s6
	v_and_or_b32 v4, v4, s3, v3
	v_bfe_u32 v3, v14, 16, 1
	v_add3_u32 v3, v14, v3, s6
	v_bfe_u32 v5, v15, 16, 1
	v_lshrrev_b32_e32 v3, 16, v3
	v_add3_u32 v5, v15, v5, s6
	v_and_or_b32 v5, v5, s3, v3
	v_bfe_u32 v3, v6, 16, 1
	v_add3_u32 v3, v6, v3, s6
	v_bfe_u32 v6, v7, 16, 1
	v_lshrrev_b32_e32 v3, 16, v3
	v_add3_u32 v6, v7, v6, s6
	v_and_or_b32 v6, v6, s3, v3
	v_bfe_u32 v3, v10, 16, 1
	v_add3_u32 v3, v10, v3, s6
	v_bfe_u32 v7, v11, 16, 1
	v_lshrrev_b32_e32 v3, 16, v3
	v_add3_u32 v7, v11, v7, s6
	v_and_or_b32 v7, v7, s3, v3
	global_store_dwordx4 v[60:61], v[4:7], off offset:1792
	s_cbranch_scc1 .LBB0_2611

.LBB0_3257:
	s_or_b64 exec, exec, s[2:3]
	s_cmpk_lt_i32 s54, 0x2000
	s_waitcnt lgkmcnt(0)
	s_barrier
	s_cbranch_scc0 .LBB0_3268
	s_load_dwordx2 s[0:1], s[0:1], 0xe0
	v_and_b32_e32 v165, 15, v1
	v_mov_b32_e32 v2, 0
	v_lshlrev_b32_e32 v6, 4, v165
	v_mov_b32_e32 v7, v2
	v_lshlrev_b32_e32 v4, 5, v165
	v_lshl_add_u64 v[166:167], s[66:67], 0, v[6:7]
	v_lshlrev_b32_e32 v6, 3, v165
	v_mov_b32_e32 v5, v2
	v_mbcnt_lo_u32_b32 v3, -1, 0
	v_ashrrev_i32_e32 v179, 4, v1
	v_and_b32_e32 v164, -16, v1
	v_add_u32_e32 v1, s14, v4
	v_lshl_add_u64 v[168:169], s[68:69], 0, v[6:7]
	s_waitcnt lgkmcnt(0)
	v_lshl_add_u64 v[170:171], s[0:1], 0, v[4:5]
	v_mbcnt_hi_u32_b32 v182, -1, v3
	v_lshl_add_u32 v252, s54, 2, v179
	v_lshl_or_b32 v252, v252, 4, v165
	v_ashrrev_i32_e32 v253, 31, v252
	v_lshl_add_u64 v[252:253], v[252:253], 2, s[64:65]
	global_load_dword v250, v[252:253], off
	s_waitcnt vmcnt(0)
	v_max_i32_e32 v252, 0, v250
	v_min_u32_e32 v252, 0x10fff, v252
	v_mov_b32_e32 v253, 0
	v_lshl_add_u64 v[252:253], v[252:253], 2, s[62:63]
	global_load_dword v251, v[252:253], off
	s_waitcnt vmcnt(0)
	s_branch .LBB0_3260
.LBB0_3259:
	v_min_i32_e32 v3, 0x8000, v174
	v_and_b32_e32 v3, 0xfffff000, v3
	v_add_u32_e32 v3, v1, v3
	s_waitcnt vmcnt(1)
	v_lshlrev_b32_e32 v148, 16, v72
	v_lshlrev_b32_e32 v150, 16, v73
	v_lshlrev_b32_e32 v152, 16, v74
	v_lshlrev_b32_e32 v154, 16, v75
	v_and_b32_e32 v149, 0xffff0000, v72
	v_and_b32_e32 v151, 0xffff0000, v73
	v_and_b32_e32 v153, 0xffff0000, v74
	v_and_b32_e32 v155, 0xffff0000, v75
	ds_read_b128 v[72:75], v3
	v_lshlrev_b32_e32 v100, 16, v96
	v_lshlrev_b32_e32 v102, 16, v97
	v_and_b32_e32 v101, 0xffff0000, v96
	v_and_b32_e32 v103, 0xffff0000, v97
	v_lshlrev_b32_e32 v132, 16, v80
	v_lshlrev_b32_e32 v134, 16, v81
	v_lshlrev_b32_e32 v136, 16, v82
	v_lshlrev_b32_e32 v138, 16, v83
	v_lshlrev_b32_e32 v140, 16, v76
	v_lshlrev_b32_e32 v142, 16, v77
	v_lshlrev_b32_e32 v144, 16, v78
	v_lshlrev_b32_e32 v146, 16, v79
	s_waitcnt vmcnt(0)
	v_max_i32_e32 v252, 0, v250
	v_min_u32_e32 v252, 0x10fff, v252
	v_mov_b32_e32 v253, 0
	v_lshl_add_u64 v[252:253], v[252:253], 2, s[62:63]
	global_load_dword v251, v[252:253], off
	v_lshlrev_b32_e32 v156, 16, v64
	v_lshlrev_b32_e32 v158, 16, v65
	v_lshlrev_b32_e32 v160, 16, v66
	v_lshlrev_b32_e32 v162, 16, v67
	v_and_b32_e32 v133, 0xffff0000, v80
	v_and_b32_e32 v135, 0xffff0000, v81
	v_and_b32_e32 v137, 0xffff0000, v82
	v_and_b32_e32 v139, 0xffff0000, v83
	v_and_b32_e32 v141, 0xffff0000, v76
	v_and_b32_e32 v143, 0xffff0000, v77
	v_and_b32_e32 v145, 0xffff0000, v78
	v_and_b32_e32 v147, 0xffff0000, v79
	v_and_b32_e32 v157, 0xffff0000, v64
	v_and_b32_e32 v159, 0xffff0000, v65
	v_and_b32_e32 v161, 0xffff0000, v66
	ds_read_b128 v[76:79], v3 offset:16
	v_and_b32_e32 v163, 0xffff0000, v67
	s_waitcnt lgkmcnt(1)
	v_pk_fma_f32 v[66:67], v[70:71], v[74:75], v[102:103]
	ds_read_b128 v[80:83], v3 offset:512
	v_pk_fma_f32 v[64:65], v[68:69], v[72:73], v[100:101]
	ds_read_b128 v[68:71], v3 offset:528
	v_lshlrev_b32_e32 v104, 16, v98
	v_lshlrev_b32_e32 v106, 16, v99
	v_lshlrev_b32_e32 v112, 16, v94
	v_lshlrev_b32_e32 v114, 16, v95
	v_and_b32_e32 v105, 0xffff0000, v98
	v_and_b32_e32 v107, 0xffff0000, v99
	v_and_b32_e32 v113, 0xffff0000, v94
	v_and_b32_e32 v115, 0xffff0000, v95
	s_waitcnt lgkmcnt(2)
	v_pk_fma_f32 v[62:63], v[62:63], v[78:79], v[106:107]
	v_pk_fma_f32 v[60:61], v[60:61], v[76:77], v[104:105]
	ds_read_b128 v[72:75], v3 offset:1024
	ds_read_b128 v[76:79], v3 offset:1040
	s_waitcnt lgkmcnt(2)
	v_pk_fma_f32 v[54:55], v[54:55], v[70:71], v[114:115]
	v_pk_fma_f32 v[52:53], v[52:53], v[68:69], v[112:113]
	ds_read_b128 v[68:71], v3 offset:1536
	v_lshlrev_b32_e32 v116, 16, v88
	v_lshlrev_b32_e32 v118, 16, v89
	v_lshlrev_b32_e32 v120, 16, v90
	v_lshlrev_b32_e32 v122, 16, v91
	v_lshlrev_b32_e32 v124, 16, v84
	v_lshlrev_b32_e32 v126, 16, v85
	v_and_b32_e32 v117, 0xffff0000, v88
	v_and_b32_e32 v119, 0xffff0000, v89
	v_and_b32_e32 v121, 0xffff0000, v90
	v_and_b32_e32 v123, 0xffff0000, v91
	v_and_b32_e32 v125, 0xffff0000, v84
	v_and_b32_e32 v127, 0xffff0000, v85
	s_waitcnt lgkmcnt(2)
	v_pk_fma_f32 v[50:51], v[50:51], v[74:75], v[118:119]
	v_pk_fma_f32 v[48:49], v[48:49], v[72:73], v[116:117]
	s_waitcnt lgkmcnt(1)
	v_pk_fma_f32 v[46:47], v[46:47], v[78:79], v[122:123]
	ds_read_b128 v[72:75], v3 offset:1552
	v_pk_fma_f32 v[44:45], v[44:45], v[76:77], v[120:121]
	s_waitcnt lgkmcnt(1)
	v_pk_fma_f32 v[42:43], v[42:43], v[70:71], v[126:127]
	ds_read_b128 v[76:79], v3 offset:2048
	v_pk_fma_f32 v[40:41], v[40:41], v[68:69], v[124:125]
	ds_read_b128 v[68:71], v3 offset:2064
	v_lshlrev_b32_e32 v128, 16, v86
	v_lshlrev_b32_e32 v130, 16, v87
	v_and_b32_e32 v129, 0xffff0000, v86
	v_and_b32_e32 v131, 0xffff0000, v87
	s_waitcnt lgkmcnt(2)
	v_pk_fma_f32 v[38:39], v[38:39], v[74:75], v[130:131]
	v_pk_fma_f32 v[36:37], v[36:37], v[72:73], v[128:129]
	s_waitcnt lgkmcnt(1)
	v_pk_fma_f32 v[34:35], v[34:35], v[78:79], v[134:135]
	ds_read_b128 v[72:75], v3 offset:2560
	v_pk_fma_f32 v[32:33], v[32:33], v[76:77], v[132:133]
	s_waitcnt lgkmcnt(1)
	v_pk_fma_f32 v[30:31], v[30:31], v[70:71], v[138:139]
	ds_read_b128 v[76:79], v3 offset:2576
	v_pk_fma_f32 v[28:29], v[28:29], v[68:69], v[136:137]
	ds_read_b128 v[68:71], v3 offset:3072
	s_waitcnt lgkmcnt(2)
	v_pk_fma_f32 v[26:27], v[26:27], v[74:75], v[142:143]
	v_pk_fma_f32 v[24:25], v[24:25], v[72:73], v[140:141]
	s_waitcnt lgkmcnt(1)
	v_pk_fma_f32 v[22:23], v[22:23], v[78:79], v[146:147]
	v_pk_fma_f32 v[20:21], v[20:21], v[76:77], v[144:145]
	ds_read_b128 v[72:75], v3 offset:3088
	s_waitcnt lgkmcnt(1)
	v_pk_fma_f32 v[18:19], v[18:19], v[70:71], v[150:151]
	ds_read_b128 v[76:79], v3 offset:3584
	v_pk_fma_f32 v[16:17], v[16:17], v[68:69], v[148:149]
	ds_read_b128 v[68:71], v3 offset:3600
	s_add_i32 s54, s54, s55
	v_lshlrev_b32_e32 v108, 16, v92
	v_lshlrev_b32_e32 v110, 16, v93
	v_and_b32_e32 v109, 0xffff0000, v92
	v_and_b32_e32 v111, 0xffff0000, v93
	s_waitcnt lgkmcnt(0)
	v_pk_fma_f32 v[6:7], v[6:7], v[70:71], v[162:163]
	v_pk_fma_f32 v[4:5], v[4:5], v[68:69], v[160:161]
	v_lshl_add_u64 v[68:69], v[172:173], 2, v[170:171]
	s_cmpk_gt_i32 s54, 0x1fff
	v_pk_fma_f32 v[58:59], v[58:59], v[82:83], v[110:111]
	v_pk_fma_f32 v[56:57], v[56:57], v[80:81], v[108:109]
	v_pk_fma_f32 v[14:15], v[14:15], v[74:75], v[154:155]
	v_pk_fma_f32 v[12:13], v[12:13], v[72:73], v[152:153]
	v_pk_fma_f32 v[10:11], v[10:11], v[78:79], v[158:159]
	v_pk_fma_f32 v[8:9], v[8:9], v[76:77], v[156:157]
	global_store_dwordx4 v[68:69], v[64:67], off
	global_store_dwordx4 v[68:69], v[60:63], off offset:16
	global_store_dwordx4 v[68:69], v[56:59], off offset:512
	global_store_dwordx4 v[68:69], v[52:55], off offset:528
	global_store_dwordx4 v[68:69], v[48:51], off offset:1024
	global_store_dwordx4 v[68:69], v[44:47], off offset:1040
	global_store_dwordx4 v[68:69], v[40:43], off offset:1536
	global_store_dwordx4 v[68:69], v[36:39], off offset:1552
	global_store_dwordx4 v[68:69], v[32:35], off offset:2048
	global_store_dwordx4 v[68:69], v[28:31], off offset:2064
	global_store_dwordx4 v[68:69], v[24:27], off offset:2560
	global_store_dwordx4 v[68:69], v[20:23], off offset:2576
	global_store_dwordx4 v[68:69], v[16:19], off offset:3072
	global_store_dwordx4 v[68:69], v[12:15], off offset:3088
	global_store_dwordx4 v[68:69], v[8:11], off offset:3584
	global_store_dwordx4 v[68:69], v[4:7], off offset:3600
	s_cbranch_scc1 .LBB0_3268
.LBB0_3260:
	v_lshl_add_u32 v174, s54, 2, v179
	v_lshl_or_b32 v4, v174, 4, v165
	v_ashrrev_i32_e32 v5, 31, v4
	v_lshl_add_u64 v[4:5], v[4:5], 2, s[64:65]
	s_waitcnt vmcnt(8)
	v_mov_b32_e32 v176, v250
	v_cmp_lt_i32_e32 vcc, -1, v176
	v_cndmask_b32_e32 v177, 0, v251, vcc
	s_lshl_b32 s100, s55, 8
	s_mov_b32 s101, 0
	v_lshl_add_u64 v[252:253], v[4:5], 0, s[100:101]
	global_load_dword v250, v[252:253], off
	v_ashrrev_i32_e32 v175, 31, v174
	v_lshlrev_b64 v[4:5], 11, v[174:175]
	v_lshl_add_u64 v[4:5], v[166:167], 0, v[4:5]
	global_load_dwordx4 v[96:99], v[4:5], off
	global_load_dwordx4 v[92:95], v[4:5], off offset:256
	global_load_dwordx4 v[88:91], v[4:5], off offset:512
	global_load_dwordx4 v[84:87], v[4:5], off offset:768
	global_load_dwordx4 v[80:83], v[4:5], off offset:1024
	global_load_dwordx4 v[76:79], v[4:5], off offset:1280
	global_load_dwordx4 v[72:75], v[4:5], off offset:1536
	global_load_dwordx4 v[64:67], v[4:5], off offset:1792
	v_cndmask_b32_e64 v3, 0, 1, vcc
	v_cmp_ne_u32_e32 vcc, 0, v3
	v_lshlrev_b64 v[172:173], 10, v[174:175]
	v_mov_b32_e32 v3, v2
	v_lshrrev_b64 v[4:5], v164, vcc
	v_and_b32_e32 v175, 0xffff, v4
	v_mov_b32_e32 v4, v2
	v_mov_b32_e32 v5, v2
	v_mov_b64_e32 v[162:163], v[4:5]
	v_mov_b64_e32 v[158:159], v[4:5]
	v_mov_b64_e32 v[154:155], v[4:5]
	v_mov_b64_e32 v[150:151], v[4:5]
	v_mov_b64_e32 v[146:147], v[4:5]
	v_mov_b64_e32 v[142:143], v[4:5]
	v_mov_b64_e32 v[138:139], v[4:5]
	v_mov_b64_e32 v[134:135], v[4:5]
	v_mov_b64_e32 v[130:131], v[4:5]
	v_mov_b64_e32 v[126:127], v[4:5]
	v_mov_b64_e32 v[122:123], v[4:5]
	v_mov_b64_e32 v[118:119], v[4:5]
	v_mov_b64_e32 v[114:115], v[4:5]
	v_mov_b64_e32 v[110:111], v[4:5]
	v_mov_b64_e32 v[106:107], v[4:5]
	v_mov_b64_e32 v[102:103], v[4:5]
	v_mov_b64_e32 v[160:161], v[2:3]
	v_mov_b64_e32 v[156:157], v[2:3]
	v_mov_b64_e32 v[152:153], v[2:3]
	v_mov_b64_e32 v[148:149], v[2:3]
	v_mov_b64_e32 v[144:145], v[2:3]
	v_mov_b64_e32 v[140:141], v[2:3]
	v_mov_b64_e32 v[136:137], v[2:3]
	v_mov_b64_e32 v[132:133], v[2:3]
	v_mov_b64_e32 v[128:129], v[2:3]
	v_mov_b64_e32 v[124:125], v[2:3]
	v_mov_b64_e32 v[120:121], v[2:3]
	v_mov_b64_e32 v[116:117], v[2:3]
	v_mov_b64_e32 v[112:113], v[2:3]
	v_mov_b64_e32 v[108:109], v[2:3]
	v_mov_b64_e32 v[104:105], v[2:3]
	v_mov_b64_e32 v[100:101], v[2:3]
	s_branch .LBB0_3264

.LBB0_3264:
	v_mov_b64_e32 v[68:69], v[100:101]
	v_mov_b64_e32 v[60:61], v[104:105]
	v_mov_b64_e32 v[56:57], v[108:109]
	v_mov_b64_e32 v[52:53], v[112:113]
	v_mov_b64_e32 v[48:49], v[116:117]
	v_mov_b64_e32 v[44:45], v[120:121]
	v_mov_b64_e32 v[40:41], v[124:125]
	v_mov_b64_e32 v[36:37], v[128:129]
	v_mov_b64_e32 v[32:33], v[132:133]
	v_mov_b64_e32 v[28:29], v[136:137]
	v_mov_b64_e32 v[24:25], v[140:141]
	v_mov_b64_e32 v[20:21], v[144:145]
	v_mov_b64_e32 v[16:17], v[148:149]
	v_mov_b64_e32 v[12:13], v[152:153]
	v_mov_b64_e32 v[8:9], v[156:157]
	v_mov_b64_e32 v[4:5], v[160:161]
	v_mov_b64_e32 v[70:71], v[102:103]
	v_mov_b64_e32 v[62:63], v[106:107]
	v_mov_b64_e32 v[58:59], v[110:111]
	v_mov_b64_e32 v[54:55], v[114:115]
	v_mov_b64_e32 v[50:51], v[118:119]
	v_mov_b64_e32 v[46:47], v[122:123]
	v_mov_b64_e32 v[42:43], v[126:127]
	v_mov_b64_e32 v[38:39], v[130:131]
	v_mov_b64_e32 v[34:35], v[134:135]
	v_mov_b64_e32 v[30:31], v[138:139]
	v_mov_b64_e32 v[26:27], v[142:143]
	v_mov_b64_e32 v[22:23], v[146:147]
	v_mov_b64_e32 v[18:19], v[150:151]
	v_mov_b64_e32 v[14:15], v[154:155]
	v_mov_b64_e32 v[10:11], v[158:159]
	v_mov_b64_e32 v[6:7], v[162:163]
	v_cmp_ne_u32_e32 vcc, 0, v175
	s_cbranch_vccz .LBB0_3267
	v_ffbl_b32_e32 v3, v175
	v_cndmask_b32_e32 v3, 0, v3, vcc
	v_add_u32_e32 v3, v3, v164
	v_and_b32_e32 v3, 63, v3
	v_and_or_b32 v3, v182, 64, v3
	v_lshlrev_b32_e32 v3, 2, v3
	s_waitcnt lgkmcnt(1)
	ds_bpermute_b32 v180, v3, v176
	s_waitcnt lgkmcnt(1)
	ds_bpermute_b32 v178, v3, v177
	v_mov_b64_e32 v[102:103], v[70:71]
	v_mov_b64_e32 v[106:107], v[62:63]
	v_mov_b64_e32 v[110:111], v[58:59]
	v_mov_b64_e32 v[114:115], v[54:55]
	v_mov_b64_e32 v[118:119], v[50:51]
	v_mov_b64_e32 v[122:123], v[46:47]
	v_mov_b64_e32 v[126:127], v[42:43]
	v_mov_b64_e32 v[130:131], v[38:39]
	v_mov_b64_e32 v[134:135], v[34:35]
	v_mov_b64_e32 v[138:139], v[30:31]
	v_mov_b64_e32 v[142:143], v[26:27]
	v_mov_b64_e32 v[146:147], v[22:23]
	v_mov_b64_e32 v[150:151], v[18:19]
	v_mov_b64_e32 v[154:155], v[14:15]
	v_mov_b64_e32 v[158:159], v[10:11]
	v_mov_b64_e32 v[162:163], v[6:7]
	v_mov_b64_e32 v[100:101], v[68:69]
	v_mov_b64_e32 v[104:105], v[60:61]
	v_mov_b64_e32 v[108:109], v[56:57]
	v_mov_b64_e32 v[112:113], v[52:53]
	v_mov_b64_e32 v[116:117], v[48:49]
	v_mov_b64_e32 v[120:121], v[44:45]
	v_mov_b64_e32 v[124:125], v[40:41]
	v_mov_b64_e32 v[128:129], v[36:37]
	v_mov_b64_e32 v[132:133], v[32:33]
	v_mov_b64_e32 v[136:137], v[28:29]
	v_mov_b64_e32 v[140:141], v[24:25]
	v_mov_b64_e32 v[144:145], v[20:21]
	v_mov_b64_e32 v[148:149], v[16:17]
	v_mov_b64_e32 v[152:153], v[12:13]
	v_mov_b64_e32 v[156:157], v[8:9]
	v_mov_b64_e32 v[160:161], v[4:5]
	s_and_saveexec_b64 s[0:1], vcc
	s_xor_b64 s[0:1], exec, s[0:1]
	s_cbranch_execz .LBB0_3263
	s_waitcnt lgkmcnt(1)
	v_ashrrev_i32_e32 v181, 31, v180
	v_lshlrev_b64 v[100:101], 10, v[180:181]
	v_lshl_add_u64 v[100:101], v[168:169], 0, v[100:101]
	global_load_dwordx2 v[102:103], v[100:101], off
	global_load_dwordx2 v[104:105], v[100:101], off offset:128
	global_load_dwordx2 v[106:107], v[100:101], off offset:256
	global_load_dwordx2 v[108:109], v[100:101], off offset:384
	global_load_dwordx2 v[110:111], v[100:101], off offset:512
	global_load_dwordx2 v[112:113], v[100:101], off offset:640
	global_load_dwordx2 v[114:115], v[100:101], off offset:768
	s_nop 0
	global_load_dwordx2 v[100:101], v[100:101], off offset:896
	s_waitcnt vmcnt(7)
	v_cvt_pk_f32_fp8_e32 v[116:117], v102
	v_cvt_pk_f32_fp8_sdwa v[118:119], v102 src0_sel:WORD_1
	v_cvt_pk_f32_fp8_e32 v[120:121], v103
	v_cvt_pk_f32_fp8_sdwa v[122:123], v103 src0_sel:WORD_1
	s_waitcnt vmcnt(6)
	v_cvt_pk_f32_fp8_e32 v[124:125], v104
	v_cvt_pk_f32_fp8_sdwa v[126:127], v104 src0_sel:WORD_1
	v_cvt_pk_f32_fp8_e32 v[128:129], v105
	v_cvt_pk_f32_fp8_sdwa v[130:131], v105 src0_sel:WORD_1
	s_waitcnt vmcnt(5)
	v_cvt_pk_f32_fp8_e32 v[132:133], v106
	v_cvt_pk_f32_fp8_sdwa v[134:135], v106 src0_sel:WORD_1
	v_cvt_pk_f32_fp8_e32 v[136:137], v107
	v_cvt_pk_f32_fp8_sdwa v[138:139], v107 src0_sel:WORD_1
	s_waitcnt vmcnt(4)
	v_cvt_pk_f32_fp8_e32 v[140:141], v108
	v_cvt_pk_f32_fp8_sdwa v[142:143], v108 src0_sel:WORD_1
	v_cvt_pk_f32_fp8_e32 v[144:145], v109
	v_cvt_pk_f32_fp8_sdwa v[146:147], v109 src0_sel:WORD_1
	s_waitcnt vmcnt(3)
	v_cvt_pk_f32_fp8_e32 v[148:149], v110
	v_cvt_pk_f32_fp8_sdwa v[150:151], v110 src0_sel:WORD_1
	v_cvt_pk_f32_fp8_e32 v[152:153], v111
	v_cvt_pk_f32_fp8_sdwa v[154:155], v111 src0_sel:WORD_1
	s_waitcnt vmcnt(2)
	v_cvt_pk_f32_fp8_e32 v[156:157], v112
	v_cvt_pk_f32_fp8_sdwa v[158:159], v112 src0_sel:WORD_1
	v_cvt_pk_f32_fp8_e32 v[160:161], v113
	v_cvt_pk_f32_fp8_sdwa v[162:163], v113 src0_sel:WORD_1
	s_waitcnt vmcnt(1)
	v_cvt_pk_f32_fp8_e32 v[180:181], v114
	v_cvt_pk_f32_fp8_sdwa v[184:185], v114 src0_sel:WORD_1
	v_cvt_pk_f32_fp8_e32 v[186:187], v115
	v_cvt_pk_f32_fp8_sdwa v[188:189], v115 src0_sel:WORD_1
	s_waitcnt vmcnt(0)
	v_cvt_pk_f32_fp8_e32 v[190:191], v100
	v_cvt_pk_f32_fp8_sdwa v[192:193], v100 src0_sel:WORD_1
	v_cvt_pk_f32_fp8_e32 v[194:195], v101
	v_cvt_pk_f32_fp8_sdwa v[196:197], v101 src0_sel:WORD_1
	s_waitcnt lgkmcnt(0)
	v_pk_fma_f32 v[102:103], v[178:179], v[118:119], v[70:71] op_sel_hi:[0,1,1]
	v_pk_fma_f32 v[100:101], v[178:179], v[116:117], v[68:69] op_sel_hi:[0,1,1]
	v_pk_fma_f32 v[106:107], v[178:179], v[122:123], v[62:63] op_sel_hi:[0,1,1]
	v_pk_fma_f32 v[104:105], v[178:179], v[120:121], v[60:61] op_sel_hi:[0,1,1]
	v_pk_fma_f32 v[110:111], v[178:179], v[126:127], v[58:59] op_sel_hi:[0,1,1]
	v_pk_fma_f32 v[108:109], v[178:179], v[124:125], v[56:57] op_sel_hi:[0,1,1]
	v_pk_fma_f32 v[114:115], v[178:179], v[130:131], v[54:55] op_sel_hi:[0,1,1]
	v_pk_fma_f32 v[112:113], v[178:179], v[128:129], v[52:53] op_sel_hi:[0,1,1]
	v_pk_fma_f32 v[118:119], v[178:179], v[134:135], v[50:51] op_sel_hi:[0,1,1]
	v_pk_fma_f32 v[116:117], v[178:179], v[132:133], v[48:49] op_sel_hi:[0,1,1]
	v_pk_fma_f32 v[122:123], v[178:179], v[138:139], v[46:47] op_sel_hi:[0,1,1]
	v_pk_fma_f32 v[120:121], v[178:179], v[136:137], v[44:45] op_sel_hi:[0,1,1]
	v_pk_fma_f32 v[126:127], v[178:179], v[142:143], v[42:43] op_sel_hi:[0,1,1]
	v_pk_fma_f32 v[124:125], v[178:179], v[140:141], v[40:41] op_sel_hi:[0,1,1]
	v_pk_fma_f32 v[130:131], v[178:179], v[146:147], v[38:39] op_sel_hi:[0,1,1]
	v_pk_fma_f32 v[128:129], v[178:179], v[144:145], v[36:37] op_sel_hi:[0,1,1]
	v_pk_fma_f32 v[134:135], v[178:179], v[150:151], v[34:35] op_sel_hi:[0,1,1]
	v_pk_fma_f32 v[132:133], v[178:179], v[148:149], v[32:33] op_sel_hi:[0,1,1]
	v_pk_fma_f32 v[138:139], v[178:179], v[154:155], v[30:31] op_sel_hi:[0,1,1]
	v_pk_fma_f32 v[136:137], v[178:179], v[152:153], v[28:29] op_sel_hi:[0,1,1]
	v_pk_fma_f32 v[142:143], v[178:179], v[158:159], v[26:27] op_sel_hi:[0,1,1]
	v_pk_fma_f32 v[140:141], v[178:179], v[156:157], v[24:25] op_sel_hi:[0,1,1]
	v_pk_fma_f32 v[146:147], v[178:179], v[162:163], v[22:23] op_sel_hi:[0,1,1]
	v_pk_fma_f32 v[144:145], v[178:179], v[160:161], v[20:21] op_sel_hi:[0,1,1]
	v_pk_fma_f32 v[150:151], v[178:179], v[184:185], v[18:19] op_sel_hi:[0,1,1]
	v_pk_fma_f32 v[148:149], v[178:179], v[180:181], v[16:17] op_sel_hi:[0,1,1]
	v_pk_fma_f32 v[154:155], v[178:179], v[188:189], v[14:15] op_sel_hi:[0,1,1]
	v_pk_fma_f32 v[152:153], v[178:179], v[186:187], v[12:13] op_sel_hi:[0,1,1]
	v_pk_fma_f32 v[158:159], v[178:179], v[192:193], v[10:11] op_sel_hi:[0,1,1]
	v_pk_fma_f32 v[156:157], v[178:179], v[190:191], v[8:9] op_sel_hi:[0,1,1]
	v_pk_fma_f32 v[162:163], v[178:179], v[196:197], v[6:7] op_sel_hi:[0,1,1]
	v_pk_fma_f32 v[160:161], v[178:179], v[194:195], v[4:5] op_sel_hi:[0,1,1]
	s_branch .LBB0_3263
